# P1 sigmoid epilogue tail: 4 moves + v_pk_mul + pads rewritten as two scalar multiplies in both mode variants (same arithmetic)
# speedup vs baseline: 1.0004x; 1.0004x over previous
.LBB0_204:
	s_cmp_lg_u64 s[42:43], 0
	s_cbranch_scc1 .Lsig_m1
	v_ashrrev_i32_e32 v0, 31, v202
	v_mul_lo_u32 v174, s57, v202
	v_mul_lo_u32 v0, s56, v0
	v_mad_u64_u32 v[176:177], s[10:11], s56, v202, 0
	v_add3_u32 v177, v177, v0, v174
	v_pk_mul_f32 v[174:175], v[128:129], s[8:9] op_sel_hi:[1,0]
	v_pk_mul_f32 v[204:205], v[126:127], s[8:9] op_sel_hi:[1,0]
	v_min_f32_e32 v174, 0x41e6d4ca, v174
	v_min_f32_e32 v203, 0x41e6d4ca, v204
	v_exp_f32_e32 v207, v203
	v_min_f32_e32 v203, 0x41e6d4ca, v205
	v_exp_f32_e32 v205, v174
	v_min_f32_e32 v174, 0x41e6d4ca, v175
	v_exp_f32_e32 v206, v203
	v_exp_f32_e32 v204, v174
	v_pk_add_f32 v[174:175], v[206:207], 1.0 op_sel_hi:[1,0]
	v_pk_add_f32 v[204:205], v[204:205], 1.0 op_sel_hi:[1,0]
	v_mul_f32_e32 v206, v175, v174
	v_mul_f32_e32 v207, v205, v204
	s_nop 0
	v_mul_f32_e32 v203, v206, v207
	v_rcp_f32_e32 v203, v203
	s_nop 0
	v_mul_f32_e32 v208, v207, v203
	v_mul_f32_e32 v206, v206, v203
	v_pk_mul_f32 v[174:175], v[174:175], v[208:209] op_sel_hi:[1,0]
	v_pk_mul_f32 v[204:205], v[204:205], v[206:207] op_sel_hi:[1,0]
	s_waitcnt vmcnt(0)
	v_pk_mul_f32 v[174:175], v[142:143], v[174:175]
	v_pk_mul_f32 v[206:207], v[122:123], s[8:9] op_sel_hi:[1,0]
	s_nop 0
	v_min_f32_e32 v203, 0x41e6d4ca, v206
	v_pk_mul_f32 v[208:209], v[144:145], v[204:205]
	v_pk_mul_f32 v[204:205], v[124:125], s[8:9] op_sel_hi:[1,0]
	v_exp_f32_e32 v211, v203
	v_min_f32_e32 v203, 0x41e6d4ca, v207
	v_exp_f32_e32 v210, v203
	v_min_f32_e32 v203, 0x41e6d4ca, v204
	v_exp_f32_e32 v207, v203
	v_min_f32_e32 v203, 0x41e6d4ca, v205
	v_exp_f32_e32 v206, v203
	v_pk_add_f32 v[204:205], v[210:211], 1.0 op_sel_hi:[1,0]
	v_pk_add_f32 v[206:207], v[206:207], 1.0 op_sel_hi:[1,0]
	v_mul_f32_e32 v210, v205, v204
	v_mul_f32_e32 v211, v207, v206
	s_nop 0
	v_mul_f32_e32 v203, v210, v211
	v_rcp_f32_e32 v203, v203
	s_nop 0
	v_mul_f32_e32 v212, v211, v203
	v_mul_f32_e32 v210, v210, v203
	v_pk_mul_f32 v[204:205], v[204:205], v[212:213] op_sel_hi:[1,0]
	v_pk_mul_f32 v[206:207], v[206:207], v[210:211] op_sel_hi:[1,0]
	v_pk_mul_f32 v[212:213], v[140:141], v[206:207]
	v_pk_mul_f32 v[206:207], v[138:139], v[204:205]
	v_cvt_pk_bf16_f32 v204, v174, v175
	v_cvt_pk_bf16_f32 v205, v208, v209
	v_lshl_add_u64 v[174:175], v[170:171], 1, s[86:87]
	v_lshlrev_b64 v[208:209], 1, v[176:177]
	v_cvt_pk_bf16_f32 v206, v206, v207
	v_cvt_pk_bf16_f32 v207, v212, v213
	v_lshl_add_u64 v[176:177], v[174:175], 0, v[208:209]
	global_store_dwordx4 v[176:177], v[204:207], off
	v_pk_mul_f32 v[176:177], v[120:121], s[8:9] op_sel_hi:[1,0]
	s_nop 0
	v_pk_mul_f32 v[204:205], v[118:119], s[8:9] op_sel_hi:[1,0]
	v_min_f32_e32 v176, 0x41e6d4ca, v176
	v_min_f32_e32 v203, 0x41e6d4ca, v204
	v_exp_f32_e32 v207, v203
	v_min_f32_e32 v203, 0x41e6d4ca, v205
	v_exp_f32_e32 v205, v176
	v_min_f32_e32 v176, 0x41e6d4ca, v177
	v_exp_f32_e32 v206, v203
	v_exp_f32_e32 v204, v176
	v_pk_add_f32 v[176:177], v[206:207], 1.0 op_sel_hi:[1,0]
	v_pk_add_f32 v[204:205], v[204:205], 1.0 op_sel_hi:[1,0]
	v_mul_f32_e32 v206, v177, v176
	v_mul_f32_e32 v207, v205, v204
	s_nop 0
	v_mul_f32_e32 v203, v206, v207
	v_rcp_f32_e32 v203, v203
	s_nop 0
	v_mul_f32_e32 v210, v207, v203
	v_mul_f32_e32 v206, v206, v203
	v_pk_mul_f32 v[176:177], v[176:177], v[210:211] op_sel_hi:[1,0]
	v_pk_mul_f32 v[204:205], v[204:205], v[206:207] op_sel_hi:[1,0]
	v_pk_mul_f32 v[176:177], v[134:135], v[176:177]
	v_pk_mul_f32 v[206:207], v[114:115], s[8:9] op_sel_hi:[1,0]
	s_nop 0
	v_min_f32_e32 v203, 0x41e6d4ca, v206
	v_pk_mul_f32 v[210:211], v[136:137], v[204:205]
	v_pk_mul_f32 v[204:205], v[116:117], s[8:9] op_sel_hi:[1,0]
	v_exp_f32_e32 v213, v203
	v_min_f32_e32 v203, 0x41e6d4ca, v207
	v_exp_f32_e32 v212, v203
	v_min_f32_e32 v203, 0x41e6d4ca, v204
	v_exp_f32_e32 v207, v203
	v_min_f32_e32 v203, 0x41e6d4ca, v205
	v_exp_f32_e32 v206, v203
	v_pk_add_f32 v[204:205], v[212:213], 1.0 op_sel_hi:[1,0]
	v_pk_add_f32 v[206:207], v[206:207], 1.0 op_sel_hi:[1,0]
	v_mul_f32_e32 v212, v205, v204
	v_mul_f32_e32 v213, v207, v206
	s_nop 0
	v_mul_f32_e32 v203, v212, v213
	v_rcp_f32_e32 v203, v203
	s_nop 0
	v_mul_f32_e32 v216, v213, v203
	v_mul_f32_e32 v212, v212, v203
	v_pk_mul_f32 v[204:205], v[204:205], v[216:217] op_sel_hi:[1,0]
	v_pk_mul_f32 v[206:207], v[206:207], v[212:213] op_sel_hi:[1,0]
	v_pk_mul_f32 v[216:217], v[132:133], v[206:207]
	v_pk_mul_f32 v[206:207], v[130:131], v[204:205]
	v_cvt_pk_bf16_f32 v204, v176, v177
	v_lshl_add_u64 v[176:177], v[172:173], 1, s[86:87]
	v_cvt_pk_bf16_f32 v205, v210, v211
	v_cvt_pk_bf16_f32 v206, v206, v207
	v_cvt_pk_bf16_f32 v207, v216, v217
	v_lshl_add_u64 v[208:209], v[176:177], 0, v[208:209]
	global_store_dwordx4 v[208:209], v[204:207], off
	v_or_b32_e32 v203, 16, v202
	v_mad_u64_u32 v[208:209], s[10:11], s56, v203, 0
	v_pk_mul_f32 v[206:207], v[110:111], s[8:9] op_sel_hi:[1,0]
	v_mul_lo_u32 v204, s57, v203
	v_min_f32_e32 v203, 0x41e6d4ca, v206
	v_add3_u32 v209, v209, v0, v204
	v_pk_mul_f32 v[204:205], v[112:113], s[8:9] op_sel_hi:[1,0]
	v_exp_f32_e32 v211, v203
	v_min_f32_e32 v203, 0x41e6d4ca, v207
	v_exp_f32_e32 v210, v203
	v_min_f32_e32 v203, 0x41e6d4ca, v204
	v_exp_f32_e32 v207, v203
	v_min_f32_e32 v203, 0x41e6d4ca, v205
	v_exp_f32_e32 v206, v203
	v_pk_add_f32 v[204:205], v[210:211], 1.0 op_sel_hi:[1,0]
	v_lshlrev_b64 v[208:209], 1, v[208:209]
	v_pk_add_f32 v[206:207], v[206:207], 1.0 op_sel_hi:[1,0]
	v_mul_f32_e32 v210, v205, v204
	v_mul_f32_e32 v211, v207, v206
	s_nop 0
	v_mul_f32_e32 v203, v210, v211
	v_rcp_f32_e32 v203, v203
	s_nop 0
	v_mul_f32_e32 v212, v211, v203
	v_mul_f32_e32 v210, v210, v203
	v_pk_mul_f32 v[204:205], v[204:205], v[212:213] op_sel_hi:[1,0]
	v_pk_mul_f32 v[206:207], v[206:207], v[210:211] op_sel_hi:[1,0]
	v_pk_mul_f32 v[206:207], v[144:145], v[206:207]
	v_pk_mul_f32 v[212:213], v[106:107], s[8:9] op_sel_hi:[1,0]
	s_nop 0
	v_min_f32_e32 v203, 0x41e6d4ca, v212
	v_pk_mul_f32 v[204:205], v[142:143], v[204:205]
	v_pk_mul_f32 v[210:211], v[108:109], s[8:9] op_sel_hi:[1,0]
	v_exp_f32_e32 v217, v203
	v_min_f32_e32 v203, 0x41e6d4ca, v213
	v_exp_f32_e32 v216, v203
	v_min_f32_e32 v203, 0x41e6d4ca, v210
	v_exp_f32_e32 v213, v203
	v_min_f32_e32 v203, 0x41e6d4ca, v211
	v_exp_f32_e32 v212, v203
	v_pk_add_f32 v[210:211], v[216:217], 1.0 op_sel_hi:[1,0]
	v_cvt_pk_bf16_f32 v204, v204, v205
	v_pk_add_f32 v[212:213], v[212:213], 1.0 op_sel_hi:[1,0]
	v_mul_f32_e32 v216, v211, v210
	v_mul_f32_e32 v217, v213, v212
	v_cvt_pk_bf16_f32 v205, v206, v207
	v_mul_f32_e32 v203, v216, v217
	v_rcp_f32_e32 v203, v203
	s_nop 0
	v_mul_f32_e32 v218, v217, v203
	v_mul_f32_e32 v216, v216, v203
	v_pk_mul_f32 v[210:211], v[210:211], v[218:219] op_sel_hi:[1,0]
	v_pk_mul_f32 v[212:213], v[212:213], v[216:217] op_sel_hi:[1,0]
	v_pk_mul_f32 v[212:213], v[140:141], v[212:213]
	v_pk_mul_f32 v[210:211], v[138:139], v[210:211]
	v_cvt_pk_bf16_f32 v207, v212, v213
	v_cvt_pk_bf16_f32 v206, v210, v211
	v_lshl_add_u64 v[210:211], v[174:175], 0, v[208:209]
	global_store_dwordx4 v[210:211], v[204:207], off
	v_lshl_add_u64 v[208:209], v[176:177], 0, v[208:209]
	s_nop 0
	v_pk_mul_f32 v[206:207], v[102:103], s[8:9] op_sel_hi:[1,0]
	v_pk_mul_f32 v[204:205], v[104:105], s[8:9] op_sel_hi:[1,0]
	v_min_f32_e32 v203, 0x41e6d4ca, v206
	v_exp_f32_e32 v211, v203
	v_min_f32_e32 v203, 0x41e6d4ca, v207
	v_exp_f32_e32 v210, v203
	v_min_f32_e32 v203, 0x41e6d4ca, v204
	v_exp_f32_e32 v207, v203
	v_min_f32_e32 v203, 0x41e6d4ca, v205
	v_exp_f32_e32 v206, v203
	v_pk_add_f32 v[204:205], v[210:211], 1.0 op_sel_hi:[1,0]
	v_pk_add_f32 v[206:207], v[206:207], 1.0 op_sel_hi:[1,0]
	v_mul_f32_e32 v210, v205, v204
	v_mul_f32_e32 v211, v207, v206
	s_nop 0
	v_mul_f32_e32 v203, v210, v211
	v_rcp_f32_e32 v203, v203
	s_nop 0
	v_mul_f32_e32 v212, v211, v203
	v_mul_f32_e32 v210, v210, v203
	v_pk_mul_f32 v[204:205], v[204:205], v[212:213] op_sel_hi:[1,0]
	v_pk_mul_f32 v[206:207], v[206:207], v[210:211] op_sel_hi:[1,0]
	v_pk_mul_f32 v[206:207], v[136:137], v[206:207]
	v_pk_mul_f32 v[212:213], v[98:99], s[8:9] op_sel_hi:[1,0]
	s_nop 0
	v_min_f32_e32 v203, 0x41e6d4ca, v212
	v_pk_mul_f32 v[204:205], v[134:135], v[204:205]
	v_pk_mul_f32 v[210:211], v[100:101], s[8:9] op_sel_hi:[1,0]
	v_exp_f32_e32 v217, v203
	v_min_f32_e32 v203, 0x41e6d4ca, v213
	v_exp_f32_e32 v216, v203
	v_min_f32_e32 v203, 0x41e6d4ca, v210
	v_exp_f32_e32 v213, v203
	v_min_f32_e32 v203, 0x41e6d4ca, v211
	v_exp_f32_e32 v212, v203
	v_pk_add_f32 v[210:211], v[216:217], 1.0 op_sel_hi:[1,0]
	v_cvt_pk_bf16_f32 v204, v204, v205
	v_pk_add_f32 v[212:213], v[212:213], 1.0 op_sel_hi:[1,0]
	v_mul_f32_e32 v216, v211, v210
	v_mul_f32_e32 v217, v213, v212
	v_cvt_pk_bf16_f32 v205, v206, v207
	v_mul_f32_e32 v203, v216, v217
	v_rcp_f32_e32 v203, v203
	s_nop 0
	v_mul_f32_e32 v218, v217, v203
	v_mul_f32_e32 v216, v216, v203
	v_pk_mul_f32 v[210:211], v[210:211], v[218:219] op_sel_hi:[1,0]
	v_pk_mul_f32 v[212:213], v[212:213], v[216:217] op_sel_hi:[1,0]
	v_pk_mul_f32 v[212:213], v[132:133], v[212:213]
	v_pk_mul_f32 v[210:211], v[130:131], v[210:211]
	v_cvt_pk_bf16_f32 v207, v212, v213
	v_cvt_pk_bf16_f32 v206, v210, v211
	global_store_dwordx4 v[208:209], v[204:207], off
	v_or_b32_e32 v203, 32, v202
	v_mad_u64_u32 v[208:209], s[10:11], s56, v203, 0
	v_pk_mul_f32 v[206:207], v[94:95], s[8:9] op_sel_hi:[1,0]
	v_mul_lo_u32 v204, s57, v203
	v_min_f32_e32 v203, 0x41e6d4ca, v206
	v_add3_u32 v209, v209, v0, v204
	v_pk_mul_f32 v[204:205], v[96:97], s[8:9] op_sel_hi:[1,0]
	v_exp_f32_e32 v211, v203
	v_min_f32_e32 v203, 0x41e6d4ca, v207
	v_exp_f32_e32 v210, v203
	v_min_f32_e32 v203, 0x41e6d4ca, v204
	v_exp_f32_e32 v207, v203
	v_min_f32_e32 v203, 0x41e6d4ca, v205
	v_exp_f32_e32 v206, v203
	v_pk_add_f32 v[204:205], v[210:211], 1.0 op_sel_hi:[1,0]
	v_lshlrev_b64 v[208:209], 1, v[208:209]
	v_pk_add_f32 v[206:207], v[206:207], 1.0 op_sel_hi:[1,0]
	v_mul_f32_e32 v210, v205, v204
	v_mul_f32_e32 v211, v207, v206
	s_nop 0
	v_mul_f32_e32 v203, v210, v211
	v_rcp_f32_e32 v203, v203
	s_nop 0
	v_mul_f32_e32 v212, v211, v203
	v_mul_f32_e32 v210, v210, v203
	v_pk_mul_f32 v[204:205], v[204:205], v[212:213] op_sel_hi:[1,0]
	v_pk_mul_f32 v[206:207], v[206:207], v[210:211] op_sel_hi:[1,0]
	v_pk_mul_f32 v[206:207], v[144:145], v[206:207]
	v_pk_mul_f32 v[212:213], v[90:91], s[8:9] op_sel_hi:[1,0]
	s_nop 0
	v_min_f32_e32 v203, 0x41e6d4ca, v212
	v_pk_mul_f32 v[204:205], v[142:143], v[204:205]
	v_pk_mul_f32 v[210:211], v[92:93], s[8:9] op_sel_hi:[1,0]
	v_exp_f32_e32 v217, v203
	v_min_f32_e32 v203, 0x41e6d4ca, v213
	v_exp_f32_e32 v216, v203
	v_min_f32_e32 v203, 0x41e6d4ca, v210
	v_exp_f32_e32 v213, v203
	v_min_f32_e32 v203, 0x41e6d4ca, v211
	v_exp_f32_e32 v212, v203
	v_pk_add_f32 v[210:211], v[216:217], 1.0 op_sel_hi:[1,0]
	v_cvt_pk_bf16_f32 v204, v204, v205
	v_pk_add_f32 v[212:213], v[212:213], 1.0 op_sel_hi:[1,0]
	v_mul_f32_e32 v216, v211, v210
	v_mul_f32_e32 v217, v213, v212
	v_cvt_pk_bf16_f32 v205, v206, v207
	v_mul_f32_e32 v203, v216, v217
	v_rcp_f32_e32 v203, v203
	s_nop 0
	v_mul_f32_e32 v218, v217, v203
	v_mul_f32_e32 v216, v216, v203
	v_pk_mul_f32 v[210:211], v[210:211], v[218:219] op_sel_hi:[1,0]
	v_pk_mul_f32 v[212:213], v[212:213], v[216:217] op_sel_hi:[1,0]
	v_pk_mul_f32 v[212:213], v[140:141], v[212:213]
	v_pk_mul_f32 v[210:211], v[138:139], v[210:211]
	v_cvt_pk_bf16_f32 v207, v212, v213
	v_cvt_pk_bf16_f32 v206, v210, v211
	v_lshl_add_u64 v[210:211], v[174:175], 0, v[208:209]
	global_store_dwordx4 v[210:211], v[204:207], off
	v_lshl_add_u64 v[208:209], v[176:177], 0, v[208:209]
	s_nop 0
	v_pk_mul_f32 v[206:207], v[86:87], s[8:9] op_sel_hi:[1,0]
	v_pk_mul_f32 v[204:205], v[88:89], s[8:9] op_sel_hi:[1,0]
	v_min_f32_e32 v203, 0x41e6d4ca, v206
	v_exp_f32_e32 v211, v203
	v_min_f32_e32 v203, 0x41e6d4ca, v207
	v_exp_f32_e32 v210, v203
	v_min_f32_e32 v203, 0x41e6d4ca, v204
	v_exp_f32_e32 v207, v203
	v_min_f32_e32 v203, 0x41e6d4ca, v205
	v_exp_f32_e32 v206, v203
	v_pk_add_f32 v[204:205], v[210:211], 1.0 op_sel_hi:[1,0]
	v_pk_add_f32 v[206:207], v[206:207], 1.0 op_sel_hi:[1,0]
	v_mul_f32_e32 v210, v205, v204
	v_mul_f32_e32 v211, v207, v206
	s_nop 0
	v_mul_f32_e32 v203, v210, v211
	v_rcp_f32_e32 v203, v203
	s_nop 0
	v_mul_f32_e32 v212, v211, v203
	v_mul_f32_e32 v210, v210, v203
	v_pk_mul_f32 v[204:205], v[204:205], v[212:213] op_sel_hi:[1,0]
	v_pk_mul_f32 v[206:207], v[206:207], v[210:211] op_sel_hi:[1,0]
	v_pk_mul_f32 v[206:207], v[136:137], v[206:207]
	v_pk_mul_f32 v[212:213], v[82:83], s[8:9] op_sel_hi:[1,0]
	s_nop 0
	v_min_f32_e32 v203, 0x41e6d4ca, v212
	v_pk_mul_f32 v[204:205], v[134:135], v[204:205]
	v_pk_mul_f32 v[210:211], v[84:85], s[8:9] op_sel_hi:[1,0]
	v_exp_f32_e32 v217, v203
	v_min_f32_e32 v203, 0x41e6d4ca, v213
	v_exp_f32_e32 v216, v203
	v_min_f32_e32 v203, 0x41e6d4ca, v210
	v_exp_f32_e32 v213, v203
	v_min_f32_e32 v203, 0x41e6d4ca, v211
	v_exp_f32_e32 v212, v203
	v_pk_add_f32 v[210:211], v[216:217], 1.0 op_sel_hi:[1,0]
	v_cvt_pk_bf16_f32 v204, v204, v205
	v_pk_add_f32 v[212:213], v[212:213], 1.0 op_sel_hi:[1,0]
	v_mul_f32_e32 v216, v211, v210
	v_mul_f32_e32 v217, v213, v212
	v_cvt_pk_bf16_f32 v205, v206, v207
	v_mul_f32_e32 v203, v216, v217
	v_rcp_f32_e32 v203, v203
	s_nop 0
	v_mul_f32_e32 v218, v217, v203
	v_mul_f32_e32 v216, v216, v203
	v_pk_mul_f32 v[210:211], v[210:211], v[218:219] op_sel_hi:[1,0]
	v_pk_mul_f32 v[212:213], v[212:213], v[216:217] op_sel_hi:[1,0]
	v_pk_mul_f32 v[212:213], v[132:133], v[212:213]
	v_pk_mul_f32 v[210:211], v[130:131], v[210:211]
	v_cvt_pk_bf16_f32 v207, v212, v213
	v_cvt_pk_bf16_f32 v206, v210, v211
	v_or_b32_e32 v203, 48, v202
	global_store_dwordx4 v[208:209], v[204:207], off
	v_mad_u64_u32 v[208:209], s[10:11], s56, v203, 0
	s_nop 0
	v_mul_lo_u32 v204, s57, v203
	v_pk_mul_f32 v[206:207], v[78:79], s[8:9] op_sel_hi:[1,0]
	v_add3_u32 v209, v209, v0, v204
	v_min_f32_e32 v0, 0x41e6d4ca, v206
	v_pk_mul_f32 v[204:205], v[80:81], s[8:9] op_sel_hi:[1,0]
	v_exp_f32_e32 v211, v0
	v_min_f32_e32 v0, 0x41e6d4ca, v207
	v_exp_f32_e32 v210, v0
	v_min_f32_e32 v0, 0x41e6d4ca, v204
	v_exp_f32_e32 v207, v0
	v_min_f32_e32 v0, 0x41e6d4ca, v205
	v_exp_f32_e32 v206, v0
	v_pk_add_f32 v[204:205], v[210:211], 1.0 op_sel_hi:[1,0]
	v_lshlrev_b64 v[208:209], 1, v[208:209]
	v_pk_add_f32 v[206:207], v[206:207], 1.0 op_sel_hi:[1,0]
	v_mul_f32_e32 v210, v205, v204
	v_mul_f32_e32 v211, v207, v206
	v_mul_f32_e32 v0, v210, v211
	v_rcp_f32_e32 v203, v0
	s_nop 0
	v_mul_f32_e32 v210, v210, v203
	v_pk_mul_f32 v[206:207], v[206:207], v[210:211] op_sel_hi:[1,0]
	v_mul_f32_e32 v0, v211, v203
	v_pk_mul_f32 v[206:207], v[144:145], v[206:207]
	v_pk_mul_f32 v[212:213], v[74:75], s[8:9] op_sel_hi:[1,0]
	v_pk_mul_f32 v[204:205], v[204:205], v[0:1] op_sel_hi:[1,0]
	v_min_f32_e32 v0, 0x41e6d4ca, v212
	v_pk_mul_f32 v[204:205], v[142:143], v[204:205]
	v_pk_mul_f32 v[210:211], v[76:77], s[8:9] op_sel_hi:[1,0]
	v_exp_f32_e32 v217, v0
	v_min_f32_e32 v0, 0x41e6d4ca, v213
	v_exp_f32_e32 v216, v0
	v_min_f32_e32 v0, 0x41e6d4ca, v210
	v_exp_f32_e32 v213, v0
	v_min_f32_e32 v0, 0x41e6d4ca, v211
	v_exp_f32_e32 v212, v0
	v_pk_add_f32 v[210:211], v[216:217], 1.0 op_sel_hi:[1,0]
	v_cvt_pk_bf16_f32 v204, v204, v205
	v_pk_add_f32 v[212:213], v[212:213], 1.0 op_sel_hi:[1,0]
	v_mul_f32_e32 v216, v211, v210
	v_mul_f32_e32 v217, v213, v212
	v_mul_f32_e32 v0, v216, v217
	v_rcp_f32_e32 v203, v0
	v_cvt_pk_bf16_f32 v205, v206, v207
	v_mul_f32_e32 v0, v217, v203
	v_mul_f32_e32 v216, v216, v203
	v_pk_mul_f32 v[210:211], v[210:211], v[0:1] op_sel_hi:[1,0]
	v_pk_mul_f32 v[212:213], v[212:213], v[216:217] op_sel_hi:[1,0]
	v_pk_mul_f32 v[212:213], v[140:141], v[212:213]
	v_pk_mul_f32 v[210:211], v[138:139], v[210:211]
	v_cvt_pk_bf16_f32 v207, v212, v213
	v_cvt_pk_bf16_f32 v206, v210, v211
	v_lshl_add_u64 v[210:211], v[174:175], 0, v[208:209]
	global_store_dwordx4 v[210:211], v[204:207], off
	v_lshl_add_u64 v[208:209], v[176:177], 0, v[208:209]
	s_nop 0
	v_pk_mul_f32 v[206:207], v[70:71], s[8:9] op_sel_hi:[1,0]
	v_pk_mul_f32 v[204:205], v[72:73], s[8:9] op_sel_hi:[1,0]
	v_min_f32_e32 v0, 0x41e6d4ca, v206
	v_exp_f32_e32 v211, v0
	v_min_f32_e32 v0, 0x41e6d4ca, v207
	v_exp_f32_e32 v210, v0
	v_min_f32_e32 v0, 0x41e6d4ca, v204
	v_exp_f32_e32 v207, v0
	v_min_f32_e32 v0, 0x41e6d4ca, v205
	v_exp_f32_e32 v206, v0
	v_pk_add_f32 v[204:205], v[210:211], 1.0 op_sel_hi:[1,0]
	v_pk_add_f32 v[206:207], v[206:207], 1.0 op_sel_hi:[1,0]
	v_mul_f32_e32 v210, v205, v204
	v_mul_f32_e32 v211, v207, v206
	v_mul_f32_e32 v0, v210, v211
	v_rcp_f32_e32 v203, v0
	s_nop 0
	v_mul_f32_e32 v210, v210, v203
	v_pk_mul_f32 v[206:207], v[206:207], v[210:211] op_sel_hi:[1,0]
	v_mul_f32_e32 v0, v211, v203
	v_pk_mul_f32 v[206:207], v[136:137], v[206:207]
	v_pk_mul_f32 v[212:213], v[66:67], s[8:9] op_sel_hi:[1,0]
	v_pk_mul_f32 v[204:205], v[204:205], v[0:1] op_sel_hi:[1,0]
	v_min_f32_e32 v0, 0x41e6d4ca, v212
	v_pk_mul_f32 v[204:205], v[134:135], v[204:205]
	v_pk_mul_f32 v[210:211], v[68:69], s[8:9] op_sel_hi:[1,0]
	v_exp_f32_e32 v217, v0
	v_min_f32_e32 v0, 0x41e6d4ca, v213
	v_exp_f32_e32 v216, v0
	v_min_f32_e32 v0, 0x41e6d4ca, v210
	v_exp_f32_e32 v213, v0
	v_min_f32_e32 v0, 0x41e6d4ca, v211
	v_exp_f32_e32 v212, v0
	v_pk_add_f32 v[210:211], v[216:217], 1.0 op_sel_hi:[1,0]
	v_cvt_pk_bf16_f32 v204, v204, v205
	v_pk_add_f32 v[212:213], v[212:213], 1.0 op_sel_hi:[1,0]
	v_mul_f32_e32 v216, v211, v210
	v_mul_f32_e32 v217, v213, v212
	v_mul_f32_e32 v0, v216, v217
	v_rcp_f32_e32 v203, v0
	v_cvt_pk_bf16_f32 v205, v206, v207
	v_mul_f32_e32 v0, v217, v203
	v_mul_f32_e32 v216, v216, v203
	v_pk_mul_f32 v[210:211], v[210:211], v[0:1] op_sel_hi:[1,0]
	v_pk_mul_f32 v[212:213], v[212:213], v[216:217] op_sel_hi:[1,0]
	v_pk_mul_f32 v[212:213], v[132:133], v[212:213]
	v_pk_mul_f32 v[210:211], v[130:131], v[210:211]
	v_cvt_pk_bf16_f32 v207, v212, v213
	v_cvt_pk_bf16_f32 v206, v210, v211
	v_add_u32_e32 v0, 0x80, v202
	global_store_dwordx4 v[208:209], v[204:207], off
	v_ashrrev_i32_e32 v203, 31, v0
	v_mul_lo_u32 v203, s56, v203
	v_pk_mul_f32 v[206:207], v[62:63], s[8:9] op_sel_hi:[1,0]
	v_mul_lo_u32 v204, s57, v0
	v_mad_u64_u32 v[208:209], s[10:11], s56, v0, 0
	v_min_f32_e32 v0, 0x41e6d4ca, v206
	v_add3_u32 v209, v209, v203, v204
	v_pk_mul_f32 v[204:205], v[64:65], s[8:9] op_sel_hi:[1,0]
	v_exp_f32_e32 v211, v0
	v_min_f32_e32 v0, 0x41e6d4ca, v207
	v_exp_f32_e32 v210, v0
	v_min_f32_e32 v0, 0x41e6d4ca, v204
	v_exp_f32_e32 v207, v0
	v_min_f32_e32 v0, 0x41e6d4ca, v205
	v_exp_f32_e32 v206, v0
	v_pk_add_f32 v[204:205], v[210:211], 1.0 op_sel_hi:[1,0]
	v_lshlrev_b64 v[208:209], 1, v[208:209]
	v_pk_add_f32 v[206:207], v[206:207], 1.0 op_sel_hi:[1,0]
	v_mul_f32_e32 v210, v205, v204
	v_mul_f32_e32 v211, v207, v206
	v_mul_f32_e32 v0, v210, v211
	v_rcp_f32_e32 v203, v0
	s_nop 0
	v_mul_f32_e32 v210, v210, v203
	v_pk_mul_f32 v[206:207], v[206:207], v[210:211] op_sel_hi:[1,0]
	v_mul_f32_e32 v0, v211, v203
	v_pk_mul_f32 v[206:207], v[144:145], v[206:207]
	v_pk_mul_f32 v[212:213], v[58:59], s[8:9] op_sel_hi:[1,0]
	v_pk_mul_f32 v[204:205], v[204:205], v[0:1] op_sel_hi:[1,0]
	v_min_f32_e32 v0, 0x41e6d4ca, v212
	v_pk_mul_f32 v[204:205], v[142:143], v[204:205]
	v_pk_mul_f32 v[210:211], v[60:61], s[8:9] op_sel_hi:[1,0]
	v_exp_f32_e32 v217, v0
	v_min_f32_e32 v0, 0x41e6d4ca, v213
	v_exp_f32_e32 v216, v0
	v_min_f32_e32 v0, 0x41e6d4ca, v210
	v_exp_f32_e32 v213, v0
	v_min_f32_e32 v0, 0x41e6d4ca, v211
	v_exp_f32_e32 v212, v0
	v_pk_add_f32 v[210:211], v[216:217], 1.0 op_sel_hi:[1,0]
	v_cvt_pk_bf16_f32 v204, v204, v205
	v_pk_add_f32 v[212:213], v[212:213], 1.0 op_sel_hi:[1,0]
	v_mul_f32_e32 v216, v211, v210
	v_mul_f32_e32 v217, v213, v212
	v_mul_f32_e32 v0, v216, v217
	v_rcp_f32_e32 v203, v0
	v_cvt_pk_bf16_f32 v205, v206, v207
	v_mul_f32_e32 v0, v217, v203
	v_mul_f32_e32 v216, v216, v203
	v_pk_mul_f32 v[210:211], v[210:211], v[0:1] op_sel_hi:[1,0]
	v_pk_mul_f32 v[212:213], v[212:213], v[216:217] op_sel_hi:[1,0]
	v_pk_mul_f32 v[212:213], v[140:141], v[212:213]
	v_pk_mul_f32 v[210:211], v[138:139], v[210:211]
	v_cvt_pk_bf16_f32 v207, v212, v213
	v_cvt_pk_bf16_f32 v206, v210, v211
	v_lshl_add_u64 v[210:211], v[174:175], 0, v[208:209]
	global_store_dwordx4 v[210:211], v[204:207], off
	v_lshl_add_u64 v[208:209], v[176:177], 0, v[208:209]
	s_nop 0
	v_pk_mul_f32 v[206:207], v[54:55], s[8:9] op_sel_hi:[1,0]
	v_pk_mul_f32 v[204:205], v[56:57], s[8:9] op_sel_hi:[1,0]
	v_min_f32_e32 v0, 0x41e6d4ca, v206
	v_exp_f32_e32 v211, v0
	v_min_f32_e32 v0, 0x41e6d4ca, v207
	v_exp_f32_e32 v210, v0
	v_min_f32_e32 v0, 0x41e6d4ca, v204
	v_exp_f32_e32 v207, v0
	v_min_f32_e32 v0, 0x41e6d4ca, v205
	v_exp_f32_e32 v206, v0
	v_pk_add_f32 v[204:205], v[210:211], 1.0 op_sel_hi:[1,0]
	v_pk_add_f32 v[206:207], v[206:207], 1.0 op_sel_hi:[1,0]
	v_mul_f32_e32 v210, v205, v204
	v_mul_f32_e32 v211, v207, v206
	v_mul_f32_e32 v0, v210, v211
	v_rcp_f32_e32 v203, v0
	s_nop 0
	v_mul_f32_e32 v210, v210, v203
	v_pk_mul_f32 v[206:207], v[206:207], v[210:211] op_sel_hi:[1,0]
	v_mul_f32_e32 v0, v211, v203
	v_pk_mul_f32 v[206:207], v[136:137], v[206:207]
	v_pk_mul_f32 v[212:213], v[50:51], s[8:9] op_sel_hi:[1,0]
	v_pk_mul_f32 v[204:205], v[204:205], v[0:1] op_sel_hi:[1,0]
	v_min_f32_e32 v0, 0x41e6d4ca, v212
	v_pk_mul_f32 v[204:205], v[134:135], v[204:205]
	v_pk_mul_f32 v[210:211], v[52:53], s[8:9] op_sel_hi:[1,0]
	v_exp_f32_e32 v217, v0
	v_min_f32_e32 v0, 0x41e6d4ca, v213
	v_exp_f32_e32 v216, v0
	v_min_f32_e32 v0, 0x41e6d4ca, v210
	v_exp_f32_e32 v213, v0
	v_min_f32_e32 v0, 0x41e6d4ca, v211
	v_exp_f32_e32 v212, v0
	v_pk_add_f32 v[210:211], v[216:217], 1.0 op_sel_hi:[1,0]
	v_cvt_pk_bf16_f32 v204, v204, v205
	v_pk_add_f32 v[212:213], v[212:213], 1.0 op_sel_hi:[1,0]
	v_mul_f32_e32 v216, v211, v210
	v_mul_f32_e32 v217, v213, v212
	v_mul_f32_e32 v0, v216, v217
	v_rcp_f32_e32 v203, v0
	v_cvt_pk_bf16_f32 v205, v206, v207
	v_mul_f32_e32 v0, v217, v203
	v_mul_f32_e32 v216, v216, v203
	v_pk_mul_f32 v[210:211], v[210:211], v[0:1] op_sel_hi:[1,0]
	v_pk_mul_f32 v[212:213], v[212:213], v[216:217] op_sel_hi:[1,0]
	v_pk_mul_f32 v[212:213], v[132:133], v[212:213]
	v_pk_mul_f32 v[210:211], v[130:131], v[210:211]
	v_cvt_pk_bf16_f32 v207, v212, v213
	v_cvt_pk_bf16_f32 v206, v210, v211
	v_add_u32_e32 v0, 0x90, v202
	global_store_dwordx4 v[208:209], v[204:207], off
	v_ashrrev_i32_e32 v203, 31, v0
	v_mul_lo_u32 v203, s56, v203
	v_pk_mul_f32 v[206:207], v[46:47], s[8:9] op_sel_hi:[1,0]
	v_mul_lo_u32 v204, s57, v0
	v_mad_u64_u32 v[208:209], s[10:11], s56, v0, 0
	v_min_f32_e32 v0, 0x41e6d4ca, v206
	v_add3_u32 v209, v209, v203, v204
	v_pk_mul_f32 v[204:205], v[48:49], s[8:9] op_sel_hi:[1,0]
	v_exp_f32_e32 v211, v0
	v_min_f32_e32 v0, 0x41e6d4ca, v207
	v_exp_f32_e32 v210, v0
	v_min_f32_e32 v0, 0x41e6d4ca, v204
	v_exp_f32_e32 v207, v0
	v_min_f32_e32 v0, 0x41e6d4ca, v205
	v_exp_f32_e32 v206, v0
	v_pk_add_f32 v[204:205], v[210:211], 1.0 op_sel_hi:[1,0]
	v_lshlrev_b64 v[208:209], 1, v[208:209]
	v_pk_add_f32 v[206:207], v[206:207], 1.0 op_sel_hi:[1,0]
	v_mul_f32_e32 v210, v205, v204
	v_mul_f32_e32 v211, v207, v206
	v_mul_f32_e32 v0, v210, v211
	v_rcp_f32_e32 v203, v0
	s_nop 0
	v_mul_f32_e32 v210, v210, v203
	v_pk_mul_f32 v[206:207], v[206:207], v[210:211] op_sel_hi:[1,0]
	v_mul_f32_e32 v0, v211, v203
	v_pk_mul_f32 v[206:207], v[144:145], v[206:207]
	v_pk_mul_f32 v[212:213], v[42:43], s[8:9] op_sel_hi:[1,0]
	v_pk_mul_f32 v[204:205], v[204:205], v[0:1] op_sel_hi:[1,0]
	v_min_f32_e32 v0, 0x41e6d4ca, v212
	v_pk_mul_f32 v[204:205], v[142:143], v[204:205]
	v_pk_mul_f32 v[210:211], v[44:45], s[8:9] op_sel_hi:[1,0]
	v_exp_f32_e32 v217, v0
	v_min_f32_e32 v0, 0x41e6d4ca, v213
	v_exp_f32_e32 v216, v0
	v_min_f32_e32 v0, 0x41e6d4ca, v210
	v_exp_f32_e32 v213, v0
	v_min_f32_e32 v0, 0x41e6d4ca, v211
	v_exp_f32_e32 v212, v0
	v_pk_add_f32 v[210:211], v[216:217], 1.0 op_sel_hi:[1,0]
	v_cvt_pk_bf16_f32 v204, v204, v205
	v_pk_add_f32 v[212:213], v[212:213], 1.0 op_sel_hi:[1,0]
	v_mul_f32_e32 v216, v211, v210
	v_mul_f32_e32 v217, v213, v212
	v_mul_f32_e32 v0, v216, v217
	v_rcp_f32_e32 v203, v0
	v_cvt_pk_bf16_f32 v205, v206, v207
	v_mul_f32_e32 v0, v217, v203
	v_mul_f32_e32 v216, v216, v203
	v_pk_mul_f32 v[210:211], v[210:211], v[0:1] op_sel_hi:[1,0]
	v_pk_mul_f32 v[212:213], v[212:213], v[216:217] op_sel_hi:[1,0]
	v_pk_mul_f32 v[212:213], v[140:141], v[212:213]
	v_pk_mul_f32 v[210:211], v[138:139], v[210:211]
	v_cvt_pk_bf16_f32 v207, v212, v213
	v_cvt_pk_bf16_f32 v206, v210, v211
	v_lshl_add_u64 v[210:211], v[174:175], 0, v[208:209]
	global_store_dwordx4 v[210:211], v[204:207], off
	v_lshl_add_u64 v[208:209], v[176:177], 0, v[208:209]
	s_nop 0
	v_pk_mul_f32 v[206:207], v[38:39], s[8:9] op_sel_hi:[1,0]
	v_pk_mul_f32 v[204:205], v[40:41], s[8:9] op_sel_hi:[1,0]
	v_min_f32_e32 v0, 0x41e6d4ca, v206
	v_exp_f32_e32 v211, v0
	v_min_f32_e32 v0, 0x41e6d4ca, v207
	v_exp_f32_e32 v210, v0
	v_min_f32_e32 v0, 0x41e6d4ca, v204
	v_exp_f32_e32 v207, v0
	v_min_f32_e32 v0, 0x41e6d4ca, v205
	v_exp_f32_e32 v206, v0
	v_pk_add_f32 v[204:205], v[210:211], 1.0 op_sel_hi:[1,0]
	v_pk_add_f32 v[206:207], v[206:207], 1.0 op_sel_hi:[1,0]
	v_mul_f32_e32 v210, v205, v204
	v_mul_f32_e32 v211, v207, v206
	v_mul_f32_e32 v0, v210, v211
	v_rcp_f32_e32 v203, v0
	s_nop 0
	v_mul_f32_e32 v210, v210, v203
	v_pk_mul_f32 v[206:207], v[206:207], v[210:211] op_sel_hi:[1,0]
	v_mul_f32_e32 v0, v211, v203
	v_pk_mul_f32 v[206:207], v[136:137], v[206:207]
	v_pk_mul_f32 v[212:213], v[34:35], s[8:9] op_sel_hi:[1,0]
	v_pk_mul_f32 v[204:205], v[204:205], v[0:1] op_sel_hi:[1,0]
	v_min_f32_e32 v0, 0x41e6d4ca, v212
	v_pk_mul_f32 v[204:205], v[134:135], v[204:205]
	v_pk_mul_f32 v[210:211], v[36:37], s[8:9] op_sel_hi:[1,0]
	v_exp_f32_e32 v217, v0
	v_min_f32_e32 v0, 0x41e6d4ca, v213
	v_exp_f32_e32 v216, v0
	v_min_f32_e32 v0, 0x41e6d4ca, v210
	v_exp_f32_e32 v213, v0
	v_min_f32_e32 v0, 0x41e6d4ca, v211
	v_exp_f32_e32 v212, v0
	v_pk_add_f32 v[210:211], v[216:217], 1.0 op_sel_hi:[1,0]
	v_cvt_pk_bf16_f32 v204, v204, v205
	v_pk_add_f32 v[212:213], v[212:213], 1.0 op_sel_hi:[1,0]
	v_mul_f32_e32 v216, v211, v210
	v_mul_f32_e32 v217, v213, v212
	v_mul_f32_e32 v0, v216, v217
	v_rcp_f32_e32 v203, v0
	v_cvt_pk_bf16_f32 v205, v206, v207
	v_mul_f32_e32 v0, v217, v203
	v_mul_f32_e32 v216, v216, v203
	v_pk_mul_f32 v[210:211], v[210:211], v[0:1] op_sel_hi:[1,0]
	v_pk_mul_f32 v[212:213], v[212:213], v[216:217] op_sel_hi:[1,0]
	v_pk_mul_f32 v[212:213], v[132:133], v[212:213]
	v_pk_mul_f32 v[210:211], v[130:131], v[210:211]
	v_cvt_pk_bf16_f32 v207, v212, v213
	v_cvt_pk_bf16_f32 v206, v210, v211
	v_add_u32_e32 v0, 0xa0, v202
	global_store_dwordx4 v[208:209], v[204:207], off
	v_ashrrev_i32_e32 v203, 31, v0
	v_mul_lo_u32 v203, s56, v203
	v_pk_mul_f32 v[206:207], v[30:31], s[8:9] op_sel_hi:[1,0]
	v_mul_lo_u32 v204, s57, v0
	v_mad_u64_u32 v[208:209], s[10:11], s56, v0, 0
	v_min_f32_e32 v0, 0x41e6d4ca, v206
	v_add3_u32 v209, v209, v203, v204
	v_pk_mul_f32 v[204:205], v[32:33], s[8:9] op_sel_hi:[1,0]
	v_exp_f32_e32 v211, v0
	v_min_f32_e32 v0, 0x41e6d4ca, v207
	v_exp_f32_e32 v210, v0
	v_min_f32_e32 v0, 0x41e6d4ca, v204
	v_exp_f32_e32 v207, v0
	v_min_f32_e32 v0, 0x41e6d4ca, v205
	v_exp_f32_e32 v206, v0
	v_pk_add_f32 v[204:205], v[210:211], 1.0 op_sel_hi:[1,0]
	v_lshlrev_b64 v[208:209], 1, v[208:209]
	v_pk_add_f32 v[206:207], v[206:207], 1.0 op_sel_hi:[1,0]
	v_mul_f32_e32 v210, v205, v204
	v_mul_f32_e32 v211, v207, v206
	v_mul_f32_e32 v0, v210, v211
	v_rcp_f32_e32 v203, v0
	v_lshl_add_u64 v[176:177], v[176:177], 0, v[208:209]
	v_mul_f32_e32 v210, v210, v203
	v_pk_mul_f32 v[206:207], v[206:207], v[210:211] op_sel_hi:[1,0]
	v_mul_f32_e32 v0, v211, v203
	v_pk_mul_f32 v[206:207], v[144:145], v[206:207]
	v_pk_mul_f32 v[212:213], v[26:27], s[8:9] op_sel_hi:[1,0]
	v_pk_mul_f32 v[204:205], v[204:205], v[0:1] op_sel_hi:[1,0]
	v_min_f32_e32 v0, 0x41e6d4ca, v212
	v_pk_mul_f32 v[204:205], v[142:143], v[204:205]
	v_pk_mul_f32 v[210:211], v[28:29], s[8:9] op_sel_hi:[1,0]
	v_exp_f32_e32 v217, v0
	v_min_f32_e32 v0, 0x41e6d4ca, v213
	v_exp_f32_e32 v216, v0
	v_min_f32_e32 v0, 0x41e6d4ca, v210
	v_exp_f32_e32 v213, v0
	v_min_f32_e32 v0, 0x41e6d4ca, v211
	v_exp_f32_e32 v212, v0
	v_pk_add_f32 v[210:211], v[216:217], 1.0 op_sel_hi:[1,0]
	v_cvt_pk_bf16_f32 v204, v204, v205
	v_pk_add_f32 v[212:213], v[212:213], 1.0 op_sel_hi:[1,0]
	v_mul_f32_e32 v216, v211, v210
	v_mul_f32_e32 v217, v213, v212
	v_mul_f32_e32 v0, v216, v217
	v_rcp_f32_e32 v203, v0
	v_cvt_pk_bf16_f32 v205, v206, v207
	v_mul_f32_e32 v0, v217, v203
	v_mul_f32_e32 v216, v216, v203
	v_pk_mul_f32 v[210:211], v[210:211], v[0:1] op_sel_hi:[1,0]
	v_pk_mul_f32 v[212:213], v[212:213], v[216:217] op_sel_hi:[1,0]
	v_pk_mul_f32 v[212:213], v[140:141], v[212:213]
	v_pk_mul_f32 v[210:211], v[138:139], v[210:211]
	v_cvt_pk_bf16_f32 v207, v212, v213
	v_cvt_pk_bf16_f32 v206, v210, v211
	v_lshl_add_u64 v[210:211], v[174:175], 0, v[208:209]
	global_store_dwordx4 v[210:211], v[204:207], off
	s_nop 1
	v_pk_mul_f32 v[206:207], v[22:23], s[8:9] op_sel_hi:[1,0]
	v_pk_mul_f32 v[204:205], v[24:25], s[8:9] op_sel_hi:[1,0]
	v_min_f32_e32 v0, 0x41e6d4ca, v206
	v_exp_f32_e32 v211, v0
	v_min_f32_e32 v0, 0x41e6d4ca, v207
	v_exp_f32_e32 v210, v0
	v_min_f32_e32 v0, 0x41e6d4ca, v204
	v_exp_f32_e32 v207, v0
	v_min_f32_e32 v0, 0x41e6d4ca, v205
	v_exp_f32_e32 v206, v0
	v_pk_add_f32 v[204:205], v[210:211], 1.0 op_sel_hi:[1,0]
	v_pk_add_f32 v[206:207], v[206:207], 1.0 op_sel_hi:[1,0]
	v_mul_f32_e32 v210, v205, v204
	v_mul_f32_e32 v211, v207, v206
	v_mul_f32_e32 v0, v210, v211
	v_rcp_f32_e32 v203, v0
	s_nop 0
	v_mul_f32_e32 v210, v210, v203
	v_pk_mul_f32 v[206:207], v[206:207], v[210:211] op_sel_hi:[1,0]
	v_mul_f32_e32 v0, v211, v203
	v_pk_mul_f32 v[206:207], v[136:137], v[206:207]
	v_pk_mul_f32 v[212:213], v[18:19], s[8:9] op_sel_hi:[1,0]
	v_pk_mul_f32 v[204:205], v[204:205], v[0:1] op_sel_hi:[1,0]
	v_min_f32_e32 v0, 0x41e6d4ca, v212
	v_pk_mul_f32 v[204:205], v[134:135], v[204:205]
	v_pk_mul_f32 v[210:211], v[20:21], s[8:9] op_sel_hi:[1,0]
	v_exp_f32_e32 v217, v0
	v_min_f32_e32 v0, 0x41e6d4ca, v213
	v_exp_f32_e32 v216, v0
	v_min_f32_e32 v0, 0x41e6d4ca, v210
	v_exp_f32_e32 v213, v0
	v_min_f32_e32 v0, 0x41e6d4ca, v211
	v_exp_f32_e32 v212, v0
	v_pk_add_f32 v[210:211], v[216:217], 1.0 op_sel_hi:[1,0]
	v_cvt_pk_bf16_f32 v204, v204, v205
	v_pk_add_f32 v[212:213], v[212:213], 1.0 op_sel_hi:[1,0]
	v_mul_f32_e32 v216, v211, v210
	v_mul_f32_e32 v217, v213, v212
	v_mul_f32_e32 v0, v216, v217
	v_rcp_f32_e32 v203, v0
	v_cvt_pk_bf16_f32 v205, v206, v207
	v_mul_f32_e32 v0, v217, v203
	v_mul_f32_e32 v216, v216, v203
	v_pk_mul_f32 v[210:211], v[210:211], v[0:1] op_sel_hi:[1,0]
	v_pk_mul_f32 v[212:213], v[212:213], v[216:217] op_sel_hi:[1,0]
	v_pk_mul_f32 v[212:213], v[132:133], v[212:213]
	v_pk_mul_f32 v[210:211], v[130:131], v[210:211]
	v_cvt_pk_bf16_f32 v207, v212, v213
	v_cvt_pk_bf16_f32 v206, v210, v211
	v_add_u32_e32 v0, 0xb0, v202
	global_store_dwordx4 v[176:177], v[204:207], off
	v_ashrrev_i32_e32 v176, 31, v0
	v_mul_lo_u32 v203, s56, v176
	v_pk_mul_f32 v[206:207], v[14:15], s[8:9] op_sel_hi:[1,0]
	v_mul_lo_u32 v204, s57, v0
	v_mad_u64_u32 v[176:177], s[10:11], s56, v0, 0
	v_min_f32_e32 v0, 0x41e6d4ca, v206
	v_add3_u32 v177, v177, v203, v204
	v_pk_mul_f32 v[204:205], v[16:17], s[8:9] op_sel_hi:[1,0]
	v_exp_f32_e32 v209, v0
	v_min_f32_e32 v0, 0x41e6d4ca, v207
	v_exp_f32_e32 v208, v0
	v_min_f32_e32 v0, 0x41e6d4ca, v204
	v_exp_f32_e32 v207, v0
	v_min_f32_e32 v0, 0x41e6d4ca, v205
	v_exp_f32_e32 v206, v0
	v_pk_add_f32 v[204:205], v[208:209], 1.0 op_sel_hi:[1,0]
	v_pk_add_f32 v[206:207], v[206:207], 1.0 op_sel_hi:[1,0]
	v_mul_f32_e32 v208, v205, v204
	v_mul_f32_e32 v209, v207, v206
	v_mul_f32_e32 v0, v208, v209
	v_rcp_f32_e32 v203, v0
	s_nop 0
	v_mul_f32_e32 v208, v208, v203
	v_pk_mul_f32 v[206:207], v[206:207], v[208:209] op_sel_hi:[1,0]
	v_mul_f32_e32 v0, v209, v203
	v_pk_mul_f32 v[144:145], v[144:145], v[206:207]
	v_pk_mul_f32 v[206:207], v[10:11], s[8:9] op_sel_hi:[1,0]
	v_pk_mul_f32 v[204:205], v[204:205], v[0:1] op_sel_hi:[1,0]
	v_min_f32_e32 v0, 0x41e6d4ca, v206
	v_pk_mul_f32 v[142:143], v[142:143], v[204:205]
	v_pk_mul_f32 v[204:205], v[12:13], s[8:9] op_sel_hi:[1,0]
	v_exp_f32_e32 v209, v0
	v_min_f32_e32 v0, 0x41e6d4ca, v207
	v_exp_f32_e32 v208, v0
	v_min_f32_e32 v0, 0x41e6d4ca, v204
	v_exp_f32_e32 v207, v0
	v_min_f32_e32 v0, 0x41e6d4ca, v205
	v_exp_f32_e32 v206, v0
	v_pk_add_f32 v[204:205], v[208:209], 1.0 op_sel_hi:[1,0]
	v_pk_add_f32 v[206:207], v[206:207], 1.0 op_sel_hi:[1,0]
	v_mul_f32_e32 v208, v205, v204
	s_nop 0
	v_mul_f32_e32 v209, v207, v206
	v_mul_f32_e32 v0, v208, v209
	v_rcp_f32_e32 v203, v0
	s_mov_b64 s[10:11], 0
	v_mul_f32_e32 v0, v209, v203
	v_mul_f32_e32 v208, v208, v203
	v_pk_mul_f32 v[204:205], v[204:205], v[0:1] op_sel_hi:[1,0]
	v_pk_mul_f32 v[206:207], v[206:207], v[208:209] op_sel_hi:[1,0]
	s_nop 0
	v_pk_mul_f32 v[206:207], v[140:141], v[206:207]
	v_pk_mul_f32 v[140:141], v[138:139], v[204:205]
	v_cvt_pk_bf16_f32 v138, v142, v143
	v_cvt_pk_bf16_f32 v139, v144, v145
	v_cvt_pk_bf16_f32 v140, v140, v141
	v_cvt_pk_bf16_f32 v141, v206, v207
	v_lshl_add_u64 v[142:143], v[176:177], 1, v[174:175]
	global_store_dwordx4 v[142:143], v[138:141], off
	s_nop 1
	v_pk_mul_f32 v[140:141], v[6:7], s[8:9] op_sel_hi:[1,0]
	v_pk_mul_f32 v[138:139], v[8:9], s[8:9] op_sel_hi:[1,0]
	v_min_f32_e32 v0, 0x41e6d4ca, v140
	v_exp_f32_e32 v143, v0
	v_min_f32_e32 v0, 0x41e6d4ca, v141
	v_exp_f32_e32 v142, v0
	v_min_f32_e32 v0, 0x41e6d4ca, v138
	v_exp_f32_e32 v141, v0
	v_min_f32_e32 v0, 0x41e6d4ca, v139
	v_exp_f32_e32 v140, v0
	v_pk_add_f32 v[138:139], v[142:143], 1.0 op_sel_hi:[1,0]
	v_pk_add_f32 v[140:141], v[140:141], 1.0 op_sel_hi:[1,0]
	v_mul_f32_e32 v142, v139, v138
	v_mul_f32_e32 v143, v141, v140
	s_nop 0
	v_mul_f32_e32 v0, v142, v143
	v_rcp_f32_e32 v144, v0
	s_nop 0
	v_mul_f32_e32 v0, v143, v144
	v_pk_mul_f32 v[138:139], v[138:139], v[0:1] op_sel_hi:[1,0]
	v_mul_f32_e32 v142, v142, v144
	v_pk_mul_f32 v[134:135], v[134:135], v[138:139]
	v_pk_mul_f32 v[138:139], v[2:3], s[8:9] op_sel_hi:[1,0]
	v_pk_mul_f32 v[140:141], v[140:141], v[142:143] op_sel_hi:[1,0]
	v_min_f32_e32 v0, 0x41e6d4ca, v138
	v_pk_mul_f32 v[140:141], v[136:137], v[140:141]
	v_pk_mul_f32 v[136:137], v[4:5], s[8:9] op_sel_hi:[1,0]
	v_exp_f32_e32 v143, v0
	v_min_f32_e32 v0, 0x41e6d4ca, v139
	v_exp_f32_e32 v142, v0
	v_min_f32_e32 v0, 0x41e6d4ca, v136
	v_exp_f32_e32 v139, v0
	v_min_f32_e32 v0, 0x41e6d4ca, v137
	v_exp_f32_e32 v138, v0
	v_pk_add_f32 v[136:137], v[142:143], 1.0 op_sel_hi:[1,0]
	v_pk_add_f32 v[138:139], v[138:139], 1.0 op_sel_hi:[1,0]
	v_mul_f32_e32 v142, v137, v136
	v_mul_f32_e32 v143, v139, v138
	s_nop 0
	v_mul_f32_e32 v0, v142, v143
	v_rcp_f32_e32 v144, v0
	s_nop 0
	v_mul_f32_e32 v0, v143, v144
	v_mul_f32_e32 v142, v142, v144
	v_pk_mul_f32 v[144:145], v[136:137], v[0:1] op_sel_hi:[1,0]
	v_pk_mul_f32 v[136:137], v[138:139], v[142:143] op_sel_hi:[1,0]
	s_nop 0
	v_pk_mul_f32 v[136:137], v[132:133], v[136:137]
	v_pk_mul_f32 v[132:133], v[130:131], v[144:145]
	v_cvt_pk_bf16_f32 v130, v134, v135
	v_cvt_pk_bf16_f32 v131, v140, v141
	v_cvt_pk_bf16_f32 v132, v132, v133
	s_branch .LBB0_205
.Lsig_m1:
	v_ashrrev_i32_e32 v0, 31, v202
	v_mul_lo_u32 v174, s57, v202
	v_mul_lo_u32 v0, s56, v0
	v_mad_u64_u32 v[176:177], s[10:11], s56, v202, 0
	v_add3_u32 v177, v177, v0, v174
	v_pk_mul_f32 v[174:175], v[128:129], s[8:9] op_sel_hi:[1,0]
	v_pk_mul_f32 v[204:205], v[126:127], s[8:9] op_sel_hi:[1,0]
	v_min_f32_e32 v174, 0x41e6d4ca, v174
	v_min_f32_e32 v203, 0x41e6d4ca, v204
	v_exp_f32_e32 v207, v203
	v_min_f32_e32 v203, 0x41e6d4ca, v205
	v_exp_f32_e32 v205, v174
	v_min_f32_e32 v174, 0x41e6d4ca, v175
	v_exp_f32_e32 v206, v203
	v_exp_f32_e32 v204, v174
	v_pk_add_f32 v[174:175], v[206:207], 1.0 op_sel_hi:[1,0]
	v_pk_add_f32 v[204:205], v[204:205], 1.0 op_sel_hi:[1,0]
	v_mul_f32_e32 v206, v175, v174
	v_mul_f32_e32 v207, v205, v204
	s_nop 0
	v_mul_f32_e32 v203, v206, v207
	v_rcp_f32_e32 v203, v203
	s_nop 0
	v_mul_f32_e32 v208, v207, v203
	v_mul_f32_e32 v206, v206, v203
	v_pk_mul_f32 v[174:175], v[174:175], v[208:209] op_sel_hi:[1,0]
	v_pk_mul_f32 v[204:205], v[204:205], v[206:207] op_sel_hi:[1,0]
	v_pk_mul_f32 v[174:175], v[126:127], v[174:175]
	v_pk_mul_f32 v[206:207], v[122:123], s[8:9] op_sel_hi:[1,0]
	s_nop 0
	v_min_f32_e32 v203, 0x41e6d4ca, v206
	v_pk_mul_f32 v[208:209], v[128:129], v[204:205]
	v_pk_mul_f32 v[204:205], v[124:125], s[8:9] op_sel_hi:[1,0]
	v_exp_f32_e32 v211, v203
	v_min_f32_e32 v203, 0x41e6d4ca, v207
	v_exp_f32_e32 v210, v203
	v_min_f32_e32 v203, 0x41e6d4ca, v204
	v_exp_f32_e32 v207, v203
	v_min_f32_e32 v203, 0x41e6d4ca, v205
	v_exp_f32_e32 v206, v203
	v_pk_add_f32 v[204:205], v[210:211], 1.0 op_sel_hi:[1,0]
	v_pk_add_f32 v[206:207], v[206:207], 1.0 op_sel_hi:[1,0]
	v_mul_f32_e32 v210, v205, v204
	v_mul_f32_e32 v211, v207, v206
	s_nop 0
	v_mul_f32_e32 v203, v210, v211
	v_rcp_f32_e32 v203, v203
	s_nop 0
	v_mul_f32_e32 v212, v211, v203
	v_mul_f32_e32 v210, v210, v203
	v_pk_mul_f32 v[204:205], v[204:205], v[212:213] op_sel_hi:[1,0]
	v_pk_mul_f32 v[206:207], v[206:207], v[210:211] op_sel_hi:[1,0]
	v_pk_mul_f32 v[212:213], v[124:125], v[206:207]
	v_pk_mul_f32 v[206:207], v[122:123], v[204:205]
	v_cvt_pk_bf16_f32 v204, v174, v175
	v_cvt_pk_bf16_f32 v205, v208, v209
	v_lshl_add_u64 v[174:175], v[170:171], 1, s[86:87]
	v_lshlrev_b64 v[208:209], 1, v[176:177]
	v_cvt_pk_bf16_f32 v206, v206, v207
	v_cvt_pk_bf16_f32 v207, v212, v213
	v_lshl_add_u64 v[176:177], v[174:175], 0, v[208:209]
	global_store_dwordx4 v[176:177], v[204:207], off
	v_pk_mul_f32 v[176:177], v[120:121], s[8:9] op_sel_hi:[1,0]
	s_nop 0
	v_pk_mul_f32 v[204:205], v[118:119], s[8:9] op_sel_hi:[1,0]
	v_min_f32_e32 v176, 0x41e6d4ca, v176
	v_min_f32_e32 v203, 0x41e6d4ca, v204
	v_exp_f32_e32 v207, v203
	v_min_f32_e32 v203, 0x41e6d4ca, v205
	v_exp_f32_e32 v205, v176
	v_min_f32_e32 v176, 0x41e6d4ca, v177
	v_exp_f32_e32 v206, v203
	v_exp_f32_e32 v204, v176
	v_pk_add_f32 v[176:177], v[206:207], 1.0 op_sel_hi:[1,0]
	v_pk_add_f32 v[204:205], v[204:205], 1.0 op_sel_hi:[1,0]
	v_mul_f32_e32 v206, v177, v176
	v_mul_f32_e32 v207, v205, v204
	s_nop 0
	v_mul_f32_e32 v203, v206, v207
	v_rcp_f32_e32 v203, v203
	s_nop 0
	v_mul_f32_e32 v210, v207, v203
	v_mul_f32_e32 v206, v206, v203
	v_pk_mul_f32 v[176:177], v[176:177], v[210:211] op_sel_hi:[1,0]
	v_pk_mul_f32 v[204:205], v[204:205], v[206:207] op_sel_hi:[1,0]
	v_pk_mul_f32 v[176:177], v[118:119], v[176:177]
	v_pk_mul_f32 v[206:207], v[114:115], s[8:9] op_sel_hi:[1,0]
	s_nop 0
	v_min_f32_e32 v203, 0x41e6d4ca, v206
	v_pk_mul_f32 v[210:211], v[120:121], v[204:205]
	v_pk_mul_f32 v[204:205], v[116:117], s[8:9] op_sel_hi:[1,0]
	v_exp_f32_e32 v213, v203
	v_min_f32_e32 v203, 0x41e6d4ca, v207
	v_exp_f32_e32 v212, v203
	v_min_f32_e32 v203, 0x41e6d4ca, v204
	v_exp_f32_e32 v207, v203
	v_min_f32_e32 v203, 0x41e6d4ca, v205
	v_exp_f32_e32 v206, v203
	v_pk_add_f32 v[204:205], v[212:213], 1.0 op_sel_hi:[1,0]
	v_pk_add_f32 v[206:207], v[206:207], 1.0 op_sel_hi:[1,0]
	v_mul_f32_e32 v212, v205, v204
	v_mul_f32_e32 v213, v207, v206
	s_nop 0
	v_mul_f32_e32 v203, v212, v213
	v_rcp_f32_e32 v203, v203
	s_nop 0
	v_mul_f32_e32 v216, v213, v203
	v_mul_f32_e32 v212, v212, v203
	v_pk_mul_f32 v[204:205], v[204:205], v[216:217] op_sel_hi:[1,0]
	v_pk_mul_f32 v[206:207], v[206:207], v[212:213] op_sel_hi:[1,0]
	v_pk_mul_f32 v[216:217], v[116:117], v[206:207]
	v_pk_mul_f32 v[206:207], v[114:115], v[204:205]
	v_cvt_pk_bf16_f32 v204, v176, v177
	v_lshl_add_u64 v[176:177], v[172:173], 1, s[86:87]
	v_cvt_pk_bf16_f32 v205, v210, v211
	v_cvt_pk_bf16_f32 v206, v206, v207
	v_cvt_pk_bf16_f32 v207, v216, v217
	v_lshl_add_u64 v[208:209], v[176:177], 0, v[208:209]
	global_store_dwordx4 v[208:209], v[204:207], off
	v_or_b32_e32 v203, 16, v202
	v_mad_u64_u32 v[208:209], s[10:11], s56, v203, 0
	v_pk_mul_f32 v[206:207], v[110:111], s[8:9] op_sel_hi:[1,0]
	v_mul_lo_u32 v204, s57, v203
	v_min_f32_e32 v203, 0x41e6d4ca, v206
	v_add3_u32 v209, v209, v0, v204
	v_pk_mul_f32 v[204:205], v[112:113], s[8:9] op_sel_hi:[1,0]
	v_exp_f32_e32 v211, v203
	v_min_f32_e32 v203, 0x41e6d4ca, v207
	v_exp_f32_e32 v210, v203
	v_min_f32_e32 v203, 0x41e6d4ca, v204
	v_exp_f32_e32 v207, v203
	v_min_f32_e32 v203, 0x41e6d4ca, v205
	v_exp_f32_e32 v206, v203
	v_pk_add_f32 v[204:205], v[210:211], 1.0 op_sel_hi:[1,0]
	v_lshlrev_b64 v[208:209], 1, v[208:209]
	v_pk_add_f32 v[206:207], v[206:207], 1.0 op_sel_hi:[1,0]
	v_mul_f32_e32 v210, v205, v204
	v_mul_f32_e32 v211, v207, v206
	s_nop 0
	v_mul_f32_e32 v203, v210, v211
	v_rcp_f32_e32 v203, v203
	s_nop 0
	v_mul_f32_e32 v212, v211, v203
	v_mul_f32_e32 v210, v210, v203
	v_pk_mul_f32 v[204:205], v[204:205], v[212:213] op_sel_hi:[1,0]
	v_pk_mul_f32 v[206:207], v[206:207], v[210:211] op_sel_hi:[1,0]
	v_pk_mul_f32 v[206:207], v[112:113], v[206:207]
	v_pk_mul_f32 v[212:213], v[106:107], s[8:9] op_sel_hi:[1,0]
	s_nop 0
	v_min_f32_e32 v203, 0x41e6d4ca, v212
	v_pk_mul_f32 v[204:205], v[110:111], v[204:205]
	v_pk_mul_f32 v[210:211], v[108:109], s[8:9] op_sel_hi:[1,0]
	v_exp_f32_e32 v217, v203
	v_min_f32_e32 v203, 0x41e6d4ca, v213
	v_exp_f32_e32 v216, v203
	v_min_f32_e32 v203, 0x41e6d4ca, v210
	v_exp_f32_e32 v213, v203
	v_min_f32_e32 v203, 0x41e6d4ca, v211
	v_exp_f32_e32 v212, v203
	v_pk_add_f32 v[210:211], v[216:217], 1.0 op_sel_hi:[1,0]
	v_cvt_pk_bf16_f32 v204, v204, v205
	v_pk_add_f32 v[212:213], v[212:213], 1.0 op_sel_hi:[1,0]
	v_mul_f32_e32 v216, v211, v210
	v_mul_f32_e32 v217, v213, v212
	v_cvt_pk_bf16_f32 v205, v206, v207
	v_mul_f32_e32 v203, v216, v217
	v_rcp_f32_e32 v203, v203
	s_nop 0
	v_mul_f32_e32 v218, v217, v203
	v_mul_f32_e32 v216, v216, v203
	v_pk_mul_f32 v[210:211], v[210:211], v[218:219] op_sel_hi:[1,0]
	v_pk_mul_f32 v[212:213], v[212:213], v[216:217] op_sel_hi:[1,0]
	v_pk_mul_f32 v[212:213], v[108:109], v[212:213]
	v_pk_mul_f32 v[210:211], v[106:107], v[210:211]
	v_cvt_pk_bf16_f32 v207, v212, v213
	v_cvt_pk_bf16_f32 v206, v210, v211
	v_lshl_add_u64 v[210:211], v[174:175], 0, v[208:209]
	global_store_dwordx4 v[210:211], v[204:207], off
	v_lshl_add_u64 v[208:209], v[176:177], 0, v[208:209]
	s_nop 0
	v_pk_mul_f32 v[206:207], v[102:103], s[8:9] op_sel_hi:[1,0]
	v_pk_mul_f32 v[204:205], v[104:105], s[8:9] op_sel_hi:[1,0]
	v_min_f32_e32 v203, 0x41e6d4ca, v206
	v_exp_f32_e32 v211, v203
	v_min_f32_e32 v203, 0x41e6d4ca, v207
	v_exp_f32_e32 v210, v203
	v_min_f32_e32 v203, 0x41e6d4ca, v204
	v_exp_f32_e32 v207, v203
	v_min_f32_e32 v203, 0x41e6d4ca, v205
	v_exp_f32_e32 v206, v203
	v_pk_add_f32 v[204:205], v[210:211], 1.0 op_sel_hi:[1,0]
	v_pk_add_f32 v[206:207], v[206:207], 1.0 op_sel_hi:[1,0]
	v_mul_f32_e32 v210, v205, v204
	v_mul_f32_e32 v211, v207, v206
	s_nop 0
	v_mul_f32_e32 v203, v210, v211
	v_rcp_f32_e32 v203, v203
	s_nop 0
	v_mul_f32_e32 v212, v211, v203
	v_mul_f32_e32 v210, v210, v203
	v_pk_mul_f32 v[204:205], v[204:205], v[212:213] op_sel_hi:[1,0]
	v_pk_mul_f32 v[206:207], v[206:207], v[210:211] op_sel_hi:[1,0]
	v_pk_mul_f32 v[206:207], v[104:105], v[206:207]
	v_pk_mul_f32 v[212:213], v[98:99], s[8:9] op_sel_hi:[1,0]
	s_nop 0
	v_min_f32_e32 v203, 0x41e6d4ca, v212
	v_pk_mul_f32 v[204:205], v[102:103], v[204:205]
	v_pk_mul_f32 v[210:211], v[100:101], s[8:9] op_sel_hi:[1,0]
	v_exp_f32_e32 v217, v203
	v_min_f32_e32 v203, 0x41e6d4ca, v213
	v_exp_f32_e32 v216, v203
	v_min_f32_e32 v203, 0x41e6d4ca, v210
	v_exp_f32_e32 v213, v203
	v_min_f32_e32 v203, 0x41e6d4ca, v211
	v_exp_f32_e32 v212, v203
	v_pk_add_f32 v[210:211], v[216:217], 1.0 op_sel_hi:[1,0]
	v_cvt_pk_bf16_f32 v204, v204, v205
	v_pk_add_f32 v[212:213], v[212:213], 1.0 op_sel_hi:[1,0]
	v_mul_f32_e32 v216, v211, v210
	v_mul_f32_e32 v217, v213, v212
	v_cvt_pk_bf16_f32 v205, v206, v207
	v_mul_f32_e32 v203, v216, v217
	v_rcp_f32_e32 v203, v203
	s_nop 0
	v_mul_f32_e32 v218, v217, v203
	v_mul_f32_e32 v216, v216, v203
	v_pk_mul_f32 v[210:211], v[210:211], v[218:219] op_sel_hi:[1,0]
	v_pk_mul_f32 v[212:213], v[212:213], v[216:217] op_sel_hi:[1,0]
	v_pk_mul_f32 v[212:213], v[100:101], v[212:213]
	v_pk_mul_f32 v[210:211], v[98:99], v[210:211]
	v_cvt_pk_bf16_f32 v207, v212, v213
	v_cvt_pk_bf16_f32 v206, v210, v211
	global_store_dwordx4 v[208:209], v[204:207], off
	v_or_b32_e32 v203, 32, v202
	v_mad_u64_u32 v[208:209], s[10:11], s56, v203, 0
	v_pk_mul_f32 v[206:207], v[94:95], s[8:9] op_sel_hi:[1,0]
	v_mul_lo_u32 v204, s57, v203
	v_min_f32_e32 v203, 0x41e6d4ca, v206
	v_add3_u32 v209, v209, v0, v204
	v_pk_mul_f32 v[204:205], v[96:97], s[8:9] op_sel_hi:[1,0]
	v_exp_f32_e32 v211, v203
	v_min_f32_e32 v203, 0x41e6d4ca, v207
	v_exp_f32_e32 v210, v203
	v_min_f32_e32 v203, 0x41e6d4ca, v204
	v_exp_f32_e32 v207, v203
	v_min_f32_e32 v203, 0x41e6d4ca, v205
	v_exp_f32_e32 v206, v203
	v_pk_add_f32 v[204:205], v[210:211], 1.0 op_sel_hi:[1,0]
	v_lshlrev_b64 v[208:209], 1, v[208:209]
	v_pk_add_f32 v[206:207], v[206:207], 1.0 op_sel_hi:[1,0]
	v_mul_f32_e32 v210, v205, v204
	v_mul_f32_e32 v211, v207, v206
	s_nop 0
	v_mul_f32_e32 v203, v210, v211
	v_rcp_f32_e32 v203, v203
	s_nop 0
	v_mul_f32_e32 v212, v211, v203
	v_mul_f32_e32 v210, v210, v203
	v_pk_mul_f32 v[204:205], v[204:205], v[212:213] op_sel_hi:[1,0]
	v_pk_mul_f32 v[206:207], v[206:207], v[210:211] op_sel_hi:[1,0]
	v_pk_mul_f32 v[206:207], v[96:97], v[206:207]
	v_pk_mul_f32 v[212:213], v[90:91], s[8:9] op_sel_hi:[1,0]
	s_nop 0
	v_min_f32_e32 v203, 0x41e6d4ca, v212
	v_pk_mul_f32 v[204:205], v[94:95], v[204:205]
	v_pk_mul_f32 v[210:211], v[92:93], s[8:9] op_sel_hi:[1,0]
	v_exp_f32_e32 v217, v203
	v_min_f32_e32 v203, 0x41e6d4ca, v213
	v_exp_f32_e32 v216, v203
	v_min_f32_e32 v203, 0x41e6d4ca, v210
	v_exp_f32_e32 v213, v203
	v_min_f32_e32 v203, 0x41e6d4ca, v211
	v_exp_f32_e32 v212, v203
	v_pk_add_f32 v[210:211], v[216:217], 1.0 op_sel_hi:[1,0]
	v_cvt_pk_bf16_f32 v204, v204, v205
	v_pk_add_f32 v[212:213], v[212:213], 1.0 op_sel_hi:[1,0]
	v_mul_f32_e32 v216, v211, v210
	v_mul_f32_e32 v217, v213, v212
	v_cvt_pk_bf16_f32 v205, v206, v207
	v_mul_f32_e32 v203, v216, v217
	v_rcp_f32_e32 v203, v203
	s_nop 0
	v_mul_f32_e32 v218, v217, v203
	v_mul_f32_e32 v216, v216, v203
	v_pk_mul_f32 v[210:211], v[210:211], v[218:219] op_sel_hi:[1,0]
	v_pk_mul_f32 v[212:213], v[212:213], v[216:217] op_sel_hi:[1,0]
	v_pk_mul_f32 v[212:213], v[92:93], v[212:213]
	v_pk_mul_f32 v[210:211], v[90:91], v[210:211]
	v_cvt_pk_bf16_f32 v207, v212, v213
	v_cvt_pk_bf16_f32 v206, v210, v211
	v_lshl_add_u64 v[210:211], v[174:175], 0, v[208:209]
	global_store_dwordx4 v[210:211], v[204:207], off
	v_lshl_add_u64 v[208:209], v[176:177], 0, v[208:209]
	s_nop 0
	v_pk_mul_f32 v[206:207], v[86:87], s[8:9] op_sel_hi:[1,0]
	v_pk_mul_f32 v[204:205], v[88:89], s[8:9] op_sel_hi:[1,0]
	v_min_f32_e32 v203, 0x41e6d4ca, v206
	v_exp_f32_e32 v211, v203
	v_min_f32_e32 v203, 0x41e6d4ca, v207
	v_exp_f32_e32 v210, v203
	v_min_f32_e32 v203, 0x41e6d4ca, v204
	v_exp_f32_e32 v207, v203
	v_min_f32_e32 v203, 0x41e6d4ca, v205
	v_exp_f32_e32 v206, v203
	v_pk_add_f32 v[204:205], v[210:211], 1.0 op_sel_hi:[1,0]
	v_pk_add_f32 v[206:207], v[206:207], 1.0 op_sel_hi:[1,0]
	v_mul_f32_e32 v210, v205, v204
	v_mul_f32_e32 v211, v207, v206
	s_nop 0
	v_mul_f32_e32 v203, v210, v211
	v_rcp_f32_e32 v203, v203
	s_nop 0
	v_mul_f32_e32 v212, v211, v203
	v_mul_f32_e32 v210, v210, v203
	v_pk_mul_f32 v[204:205], v[204:205], v[212:213] op_sel_hi:[1,0]
	v_pk_mul_f32 v[206:207], v[206:207], v[210:211] op_sel_hi:[1,0]
	v_pk_mul_f32 v[206:207], v[88:89], v[206:207]
	v_pk_mul_f32 v[212:213], v[82:83], s[8:9] op_sel_hi:[1,0]
	s_nop 0
	v_min_f32_e32 v203, 0x41e6d4ca, v212
	v_pk_mul_f32 v[204:205], v[86:87], v[204:205]
	v_pk_mul_f32 v[210:211], v[84:85], s[8:9] op_sel_hi:[1,0]
	v_exp_f32_e32 v217, v203
	v_min_f32_e32 v203, 0x41e6d4ca, v213
	v_exp_f32_e32 v216, v203
	v_min_f32_e32 v203, 0x41e6d4ca, v210
	v_exp_f32_e32 v213, v203
	v_min_f32_e32 v203, 0x41e6d4ca, v211
	v_exp_f32_e32 v212, v203
	v_pk_add_f32 v[210:211], v[216:217], 1.0 op_sel_hi:[1,0]
	v_cvt_pk_bf16_f32 v204, v204, v205
	v_pk_add_f32 v[212:213], v[212:213], 1.0 op_sel_hi:[1,0]
	v_mul_f32_e32 v216, v211, v210
	v_mul_f32_e32 v217, v213, v212
	v_cvt_pk_bf16_f32 v205, v206, v207
	v_mul_f32_e32 v203, v216, v217
	v_rcp_f32_e32 v203, v203
	s_nop 0
	v_mul_f32_e32 v218, v217, v203
	v_mul_f32_e32 v216, v216, v203
	v_pk_mul_f32 v[210:211], v[210:211], v[218:219] op_sel_hi:[1,0]
	v_pk_mul_f32 v[212:213], v[212:213], v[216:217] op_sel_hi:[1,0]
	v_pk_mul_f32 v[212:213], v[84:85], v[212:213]
	v_pk_mul_f32 v[210:211], v[82:83], v[210:211]
	v_cvt_pk_bf16_f32 v207, v212, v213
	v_cvt_pk_bf16_f32 v206, v210, v211
	v_or_b32_e32 v203, 48, v202
	global_store_dwordx4 v[208:209], v[204:207], off
	v_mad_u64_u32 v[208:209], s[10:11], s56, v203, 0
	s_nop 0
	v_mul_lo_u32 v204, s57, v203
	v_pk_mul_f32 v[206:207], v[78:79], s[8:9] op_sel_hi:[1,0]
	v_add3_u32 v209, v209, v0, v204
	v_min_f32_e32 v0, 0x41e6d4ca, v206
	v_pk_mul_f32 v[204:205], v[80:81], s[8:9] op_sel_hi:[1,0]
	v_exp_f32_e32 v211, v0
	v_min_f32_e32 v0, 0x41e6d4ca, v207
	v_exp_f32_e32 v210, v0
	v_min_f32_e32 v0, 0x41e6d4ca, v204
	v_exp_f32_e32 v207, v0
	v_min_f32_e32 v0, 0x41e6d4ca, v205
	v_exp_f32_e32 v206, v0
	v_pk_add_f32 v[204:205], v[210:211], 1.0 op_sel_hi:[1,0]
	v_lshlrev_b64 v[208:209], 1, v[208:209]
	v_pk_add_f32 v[206:207], v[206:207], 1.0 op_sel_hi:[1,0]
	v_mul_f32_e32 v210, v205, v204
	v_mul_f32_e32 v211, v207, v206
	v_mul_f32_e32 v0, v210, v211
	v_rcp_f32_e32 v203, v0
	s_nop 0
	v_mul_f32_e32 v210, v210, v203
	v_pk_mul_f32 v[206:207], v[206:207], v[210:211] op_sel_hi:[1,0]
	v_mul_f32_e32 v0, v211, v203
	v_pk_mul_f32 v[206:207], v[80:81], v[206:207]
	v_pk_mul_f32 v[212:213], v[74:75], s[8:9] op_sel_hi:[1,0]
	v_pk_mul_f32 v[204:205], v[204:205], v[0:1] op_sel_hi:[1,0]
	v_min_f32_e32 v0, 0x41e6d4ca, v212
	v_pk_mul_f32 v[204:205], v[78:79], v[204:205]
	v_pk_mul_f32 v[210:211], v[76:77], s[8:9] op_sel_hi:[1,0]
	v_exp_f32_e32 v217, v0
	v_min_f32_e32 v0, 0x41e6d4ca, v213
	v_exp_f32_e32 v216, v0
	v_min_f32_e32 v0, 0x41e6d4ca, v210
	v_exp_f32_e32 v213, v0
	v_min_f32_e32 v0, 0x41e6d4ca, v211
	v_exp_f32_e32 v212, v0
	v_pk_add_f32 v[210:211], v[216:217], 1.0 op_sel_hi:[1,0]
	v_cvt_pk_bf16_f32 v204, v204, v205
	v_pk_add_f32 v[212:213], v[212:213], 1.0 op_sel_hi:[1,0]
	v_mul_f32_e32 v216, v211, v210
	v_mul_f32_e32 v217, v213, v212
	v_mul_f32_e32 v0, v216, v217
	v_rcp_f32_e32 v203, v0
	v_cvt_pk_bf16_f32 v205, v206, v207
	v_mul_f32_e32 v0, v217, v203
	v_mul_f32_e32 v216, v216, v203
	v_pk_mul_f32 v[210:211], v[210:211], v[0:1] op_sel_hi:[1,0]
	v_pk_mul_f32 v[212:213], v[212:213], v[216:217] op_sel_hi:[1,0]
	v_pk_mul_f32 v[212:213], v[76:77], v[212:213]
	v_pk_mul_f32 v[210:211], v[74:75], v[210:211]
	v_cvt_pk_bf16_f32 v207, v212, v213
	v_cvt_pk_bf16_f32 v206, v210, v211
	v_lshl_add_u64 v[210:211], v[174:175], 0, v[208:209]
	global_store_dwordx4 v[210:211], v[204:207], off
	v_lshl_add_u64 v[208:209], v[176:177], 0, v[208:209]
	s_nop 0
	v_pk_mul_f32 v[206:207], v[70:71], s[8:9] op_sel_hi:[1,0]
	v_pk_mul_f32 v[204:205], v[72:73], s[8:9] op_sel_hi:[1,0]
	v_min_f32_e32 v0, 0x41e6d4ca, v206
	v_exp_f32_e32 v211, v0
	v_min_f32_e32 v0, 0x41e6d4ca, v207
	v_exp_f32_e32 v210, v0
	v_min_f32_e32 v0, 0x41e6d4ca, v204
	v_exp_f32_e32 v207, v0
	v_min_f32_e32 v0, 0x41e6d4ca, v205
	v_exp_f32_e32 v206, v0
	v_pk_add_f32 v[204:205], v[210:211], 1.0 op_sel_hi:[1,0]
	v_pk_add_f32 v[206:207], v[206:207], 1.0 op_sel_hi:[1,0]
	v_mul_f32_e32 v210, v205, v204
	v_mul_f32_e32 v211, v207, v206
	v_mul_f32_e32 v0, v210, v211
	v_rcp_f32_e32 v203, v0
	s_nop 0
	v_mul_f32_e32 v210, v210, v203
	v_pk_mul_f32 v[206:207], v[206:207], v[210:211] op_sel_hi:[1,0]
	v_mul_f32_e32 v0, v211, v203
	v_pk_mul_f32 v[206:207], v[72:73], v[206:207]
	v_pk_mul_f32 v[212:213], v[66:67], s[8:9] op_sel_hi:[1,0]
	v_pk_mul_f32 v[204:205], v[204:205], v[0:1] op_sel_hi:[1,0]
	v_min_f32_e32 v0, 0x41e6d4ca, v212
	v_pk_mul_f32 v[204:205], v[70:71], v[204:205]
	v_pk_mul_f32 v[210:211], v[68:69], s[8:9] op_sel_hi:[1,0]
	v_exp_f32_e32 v217, v0
	v_min_f32_e32 v0, 0x41e6d4ca, v213
	v_exp_f32_e32 v216, v0
	v_min_f32_e32 v0, 0x41e6d4ca, v210
	v_exp_f32_e32 v213, v0
	v_min_f32_e32 v0, 0x41e6d4ca, v211
	v_exp_f32_e32 v212, v0
	v_pk_add_f32 v[210:211], v[216:217], 1.0 op_sel_hi:[1,0]
	v_cvt_pk_bf16_f32 v204, v204, v205
	v_pk_add_f32 v[212:213], v[212:213], 1.0 op_sel_hi:[1,0]
	v_mul_f32_e32 v216, v211, v210
	v_mul_f32_e32 v217, v213, v212
	v_mul_f32_e32 v0, v216, v217
	v_rcp_f32_e32 v203, v0
	v_cvt_pk_bf16_f32 v205, v206, v207
	v_mul_f32_e32 v0, v217, v203
	v_mul_f32_e32 v216, v216, v203
	v_pk_mul_f32 v[210:211], v[210:211], v[0:1] op_sel_hi:[1,0]
	v_pk_mul_f32 v[212:213], v[212:213], v[216:217] op_sel_hi:[1,0]
	v_pk_mul_f32 v[212:213], v[68:69], v[212:213]
	v_pk_mul_f32 v[210:211], v[66:67], v[210:211]
	v_cvt_pk_bf16_f32 v207, v212, v213
	v_cvt_pk_bf16_f32 v206, v210, v211
	v_add_u32_e32 v0, 0x80, v202
	global_store_dwordx4 v[208:209], v[204:207], off
	v_ashrrev_i32_e32 v203, 31, v0
	v_mul_lo_u32 v203, s56, v203
	v_pk_mul_f32 v[206:207], v[62:63], s[8:9] op_sel_hi:[1,0]
	v_mul_lo_u32 v204, s57, v0
	v_mad_u64_u32 v[208:209], s[10:11], s56, v0, 0
	v_min_f32_e32 v0, 0x41e6d4ca, v206
	v_add3_u32 v209, v209, v203, v204
	v_pk_mul_f32 v[204:205], v[64:65], s[8:9] op_sel_hi:[1,0]
	v_exp_f32_e32 v211, v0
	v_min_f32_e32 v0, 0x41e6d4ca, v207
	v_exp_f32_e32 v210, v0
	v_min_f32_e32 v0, 0x41e6d4ca, v204
	v_exp_f32_e32 v207, v0
	v_min_f32_e32 v0, 0x41e6d4ca, v205
	v_exp_f32_e32 v206, v0
	v_pk_add_f32 v[204:205], v[210:211], 1.0 op_sel_hi:[1,0]
	v_lshlrev_b64 v[208:209], 1, v[208:209]
	v_pk_add_f32 v[206:207], v[206:207], 1.0 op_sel_hi:[1,0]
	v_mul_f32_e32 v210, v205, v204
	v_mul_f32_e32 v211, v207, v206
	v_mul_f32_e32 v0, v210, v211
	v_rcp_f32_e32 v203, v0
	s_nop 0
	v_mul_f32_e32 v210, v210, v203
	v_pk_mul_f32 v[206:207], v[206:207], v[210:211] op_sel_hi:[1,0]
	v_mul_f32_e32 v0, v211, v203
	v_pk_mul_f32 v[206:207], v[64:65], v[206:207]
	v_pk_mul_f32 v[212:213], v[58:59], s[8:9] op_sel_hi:[1,0]
	v_pk_mul_f32 v[204:205], v[204:205], v[0:1] op_sel_hi:[1,0]
	v_min_f32_e32 v0, 0x41e6d4ca, v212
	v_pk_mul_f32 v[204:205], v[62:63], v[204:205]
	v_pk_mul_f32 v[210:211], v[60:61], s[8:9] op_sel_hi:[1,0]
	v_exp_f32_e32 v217, v0
	v_min_f32_e32 v0, 0x41e6d4ca, v213
	v_exp_f32_e32 v216, v0
	v_min_f32_e32 v0, 0x41e6d4ca, v210
	v_exp_f32_e32 v213, v0
	v_min_f32_e32 v0, 0x41e6d4ca, v211
	v_exp_f32_e32 v212, v0
	v_pk_add_f32 v[210:211], v[216:217], 1.0 op_sel_hi:[1,0]
	v_cvt_pk_bf16_f32 v204, v204, v205
	v_pk_add_f32 v[212:213], v[212:213], 1.0 op_sel_hi:[1,0]
	v_mul_f32_e32 v216, v211, v210
	v_mul_f32_e32 v217, v213, v212
	v_mul_f32_e32 v0, v216, v217
	v_rcp_f32_e32 v203, v0
	v_cvt_pk_bf16_f32 v205, v206, v207
	v_mul_f32_e32 v0, v217, v203
	v_mul_f32_e32 v216, v216, v203
	v_pk_mul_f32 v[210:211], v[210:211], v[0:1] op_sel_hi:[1,0]
	v_pk_mul_f32 v[212:213], v[212:213], v[216:217] op_sel_hi:[1,0]
	v_pk_mul_f32 v[212:213], v[60:61], v[212:213]
	v_pk_mul_f32 v[210:211], v[58:59], v[210:211]
	v_cvt_pk_bf16_f32 v207, v212, v213
	v_cvt_pk_bf16_f32 v206, v210, v211
	v_lshl_add_u64 v[210:211], v[174:175], 0, v[208:209]
	global_store_dwordx4 v[210:211], v[204:207], off
	v_lshl_add_u64 v[208:209], v[176:177], 0, v[208:209]
	s_nop 0
	v_pk_mul_f32 v[206:207], v[54:55], s[8:9] op_sel_hi:[1,0]
	v_pk_mul_f32 v[204:205], v[56:57], s[8:9] op_sel_hi:[1,0]
	v_min_f32_e32 v0, 0x41e6d4ca, v206
	v_exp_f32_e32 v211, v0
	v_min_f32_e32 v0, 0x41e6d4ca, v207
	v_exp_f32_e32 v210, v0
	v_min_f32_e32 v0, 0x41e6d4ca, v204
	v_exp_f32_e32 v207, v0
	v_min_f32_e32 v0, 0x41e6d4ca, v205
	v_exp_f32_e32 v206, v0
	v_pk_add_f32 v[204:205], v[210:211], 1.0 op_sel_hi:[1,0]
	v_pk_add_f32 v[206:207], v[206:207], 1.0 op_sel_hi:[1,0]
	v_mul_f32_e32 v210, v205, v204
	v_mul_f32_e32 v211, v207, v206
	v_mul_f32_e32 v0, v210, v211
	v_rcp_f32_e32 v203, v0
	s_nop 0
	v_mul_f32_e32 v210, v210, v203
	v_pk_mul_f32 v[206:207], v[206:207], v[210:211] op_sel_hi:[1,0]
	v_mul_f32_e32 v0, v211, v203
	v_pk_mul_f32 v[206:207], v[56:57], v[206:207]
	v_pk_mul_f32 v[212:213], v[50:51], s[8:9] op_sel_hi:[1,0]
	v_pk_mul_f32 v[204:205], v[204:205], v[0:1] op_sel_hi:[1,0]
	v_min_f32_e32 v0, 0x41e6d4ca, v212
	v_pk_mul_f32 v[204:205], v[54:55], v[204:205]
	v_pk_mul_f32 v[210:211], v[52:53], s[8:9] op_sel_hi:[1,0]
	v_exp_f32_e32 v217, v0
	v_min_f32_e32 v0, 0x41e6d4ca, v213
	v_exp_f32_e32 v216, v0
	v_min_f32_e32 v0, 0x41e6d4ca, v210
	v_exp_f32_e32 v213, v0
	v_min_f32_e32 v0, 0x41e6d4ca, v211
	v_exp_f32_e32 v212, v0
	v_pk_add_f32 v[210:211], v[216:217], 1.0 op_sel_hi:[1,0]
	v_cvt_pk_bf16_f32 v204, v204, v205
	v_pk_add_f32 v[212:213], v[212:213], 1.0 op_sel_hi:[1,0]
	v_mul_f32_e32 v216, v211, v210
	v_mul_f32_e32 v217, v213, v212
	v_mul_f32_e32 v0, v216, v217
	v_rcp_f32_e32 v203, v0
	v_cvt_pk_bf16_f32 v205, v206, v207
	v_mul_f32_e32 v0, v217, v203
	v_mul_f32_e32 v216, v216, v203
	v_pk_mul_f32 v[210:211], v[210:211], v[0:1] op_sel_hi:[1,0]
	v_pk_mul_f32 v[212:213], v[212:213], v[216:217] op_sel_hi:[1,0]
	v_pk_mul_f32 v[212:213], v[52:53], v[212:213]
	v_pk_mul_f32 v[210:211], v[50:51], v[210:211]
	v_cvt_pk_bf16_f32 v207, v212, v213
	v_cvt_pk_bf16_f32 v206, v210, v211
	v_add_u32_e32 v0, 0x90, v202
	global_store_dwordx4 v[208:209], v[204:207], off
	v_ashrrev_i32_e32 v203, 31, v0
	v_mul_lo_u32 v203, s56, v203
	v_pk_mul_f32 v[206:207], v[46:47], s[8:9] op_sel_hi:[1,0]
	v_mul_lo_u32 v204, s57, v0
	v_mad_u64_u32 v[208:209], s[10:11], s56, v0, 0
	v_min_f32_e32 v0, 0x41e6d4ca, v206
	v_add3_u32 v209, v209, v203, v204
	v_pk_mul_f32 v[204:205], v[48:49], s[8:9] op_sel_hi:[1,0]
	v_exp_f32_e32 v211, v0
	v_min_f32_e32 v0, 0x41e6d4ca, v207
	v_exp_f32_e32 v210, v0
	v_min_f32_e32 v0, 0x41e6d4ca, v204
	v_exp_f32_e32 v207, v0
	v_min_f32_e32 v0, 0x41e6d4ca, v205
	v_exp_f32_e32 v206, v0
	v_pk_add_f32 v[204:205], v[210:211], 1.0 op_sel_hi:[1,0]
	v_lshlrev_b64 v[208:209], 1, v[208:209]
	v_pk_add_f32 v[206:207], v[206:207], 1.0 op_sel_hi:[1,0]
	v_mul_f32_e32 v210, v205, v204
	v_mul_f32_e32 v211, v207, v206
	v_mul_f32_e32 v0, v210, v211
	v_rcp_f32_e32 v203, v0
	s_nop 0
	v_mul_f32_e32 v210, v210, v203
	v_pk_mul_f32 v[206:207], v[206:207], v[210:211] op_sel_hi:[1,0]
	v_mul_f32_e32 v0, v211, v203
	v_pk_mul_f32 v[206:207], v[48:49], v[206:207]
	v_pk_mul_f32 v[212:213], v[42:43], s[8:9] op_sel_hi:[1,0]
	v_pk_mul_f32 v[204:205], v[204:205], v[0:1] op_sel_hi:[1,0]
	v_min_f32_e32 v0, 0x41e6d4ca, v212
	v_pk_mul_f32 v[204:205], v[46:47], v[204:205]
	v_pk_mul_f32 v[210:211], v[44:45], s[8:9] op_sel_hi:[1,0]
	v_exp_f32_e32 v217, v0
	v_min_f32_e32 v0, 0x41e6d4ca, v213
	v_exp_f32_e32 v216, v0
	v_min_f32_e32 v0, 0x41e6d4ca, v210
	v_exp_f32_e32 v213, v0
	v_min_f32_e32 v0, 0x41e6d4ca, v211
	v_exp_f32_e32 v212, v0
	v_pk_add_f32 v[210:211], v[216:217], 1.0 op_sel_hi:[1,0]
	v_cvt_pk_bf16_f32 v204, v204, v205
	v_pk_add_f32 v[212:213], v[212:213], 1.0 op_sel_hi:[1,0]
	v_mul_f32_e32 v216, v211, v210
	v_mul_f32_e32 v217, v213, v212
	v_mul_f32_e32 v0, v216, v217
	v_rcp_f32_e32 v203, v0
	v_cvt_pk_bf16_f32 v205, v206, v207
	v_mul_f32_e32 v0, v217, v203
	v_mul_f32_e32 v216, v216, v203
	v_pk_mul_f32 v[210:211], v[210:211], v[0:1] op_sel_hi:[1,0]
	v_pk_mul_f32 v[212:213], v[212:213], v[216:217] op_sel_hi:[1,0]
	v_pk_mul_f32 v[212:213], v[44:45], v[212:213]
	v_pk_mul_f32 v[210:211], v[42:43], v[210:211]
	v_cvt_pk_bf16_f32 v207, v212, v213
	v_cvt_pk_bf16_f32 v206, v210, v211
	v_lshl_add_u64 v[210:211], v[174:175], 0, v[208:209]
	global_store_dwordx4 v[210:211], v[204:207], off
	v_lshl_add_u64 v[208:209], v[176:177], 0, v[208:209]
	s_nop 0
	v_pk_mul_f32 v[206:207], v[38:39], s[8:9] op_sel_hi:[1,0]
	v_pk_mul_f32 v[204:205], v[40:41], s[8:9] op_sel_hi:[1,0]
	v_min_f32_e32 v0, 0x41e6d4ca, v206
	v_exp_f32_e32 v211, v0
	v_min_f32_e32 v0, 0x41e6d4ca, v207
	v_exp_f32_e32 v210, v0
	v_min_f32_e32 v0, 0x41e6d4ca, v204
	v_exp_f32_e32 v207, v0
	v_min_f32_e32 v0, 0x41e6d4ca, v205
	v_exp_f32_e32 v206, v0
	v_pk_add_f32 v[204:205], v[210:211], 1.0 op_sel_hi:[1,0]
	v_pk_add_f32 v[206:207], v[206:207], 1.0 op_sel_hi:[1,0]
	v_mul_f32_e32 v210, v205, v204
	v_mul_f32_e32 v211, v207, v206
	v_mul_f32_e32 v0, v210, v211
	v_rcp_f32_e32 v203, v0
	s_nop 0
	v_mul_f32_e32 v210, v210, v203
	v_pk_mul_f32 v[206:207], v[206:207], v[210:211] op_sel_hi:[1,0]
	v_mul_f32_e32 v0, v211, v203
	v_pk_mul_f32 v[206:207], v[40:41], v[206:207]
	v_pk_mul_f32 v[212:213], v[34:35], s[8:9] op_sel_hi:[1,0]
	v_pk_mul_f32 v[204:205], v[204:205], v[0:1] op_sel_hi:[1,0]
	v_min_f32_e32 v0, 0x41e6d4ca, v212
	v_pk_mul_f32 v[204:205], v[38:39], v[204:205]
	v_pk_mul_f32 v[210:211], v[36:37], s[8:9] op_sel_hi:[1,0]
	v_exp_f32_e32 v217, v0
	v_min_f32_e32 v0, 0x41e6d4ca, v213
	v_exp_f32_e32 v216, v0
	v_min_f32_e32 v0, 0x41e6d4ca, v210
	v_exp_f32_e32 v213, v0
	v_min_f32_e32 v0, 0x41e6d4ca, v211
	v_exp_f32_e32 v212, v0
	v_pk_add_f32 v[210:211], v[216:217], 1.0 op_sel_hi:[1,0]
	v_cvt_pk_bf16_f32 v204, v204, v205
	v_pk_add_f32 v[212:213], v[212:213], 1.0 op_sel_hi:[1,0]
	v_mul_f32_e32 v216, v211, v210
	v_mul_f32_e32 v217, v213, v212
	v_mul_f32_e32 v0, v216, v217
	v_rcp_f32_e32 v203, v0
	v_cvt_pk_bf16_f32 v205, v206, v207
	v_mul_f32_e32 v0, v217, v203
	v_mul_f32_e32 v216, v216, v203
	v_pk_mul_f32 v[210:211], v[210:211], v[0:1] op_sel_hi:[1,0]
	v_pk_mul_f32 v[212:213], v[212:213], v[216:217] op_sel_hi:[1,0]
	v_pk_mul_f32 v[212:213], v[36:37], v[212:213]
	v_pk_mul_f32 v[210:211], v[34:35], v[210:211]
	v_cvt_pk_bf16_f32 v207, v212, v213
	v_cvt_pk_bf16_f32 v206, v210, v211
	v_add_u32_e32 v0, 0xa0, v202
	global_store_dwordx4 v[208:209], v[204:207], off
	v_ashrrev_i32_e32 v203, 31, v0
	v_mul_lo_u32 v203, s56, v203
	v_pk_mul_f32 v[206:207], v[30:31], s[8:9] op_sel_hi:[1,0]
	v_mul_lo_u32 v204, s57, v0
	v_mad_u64_u32 v[208:209], s[10:11], s56, v0, 0
	v_min_f32_e32 v0, 0x41e6d4ca, v206
	v_add3_u32 v209, v209, v203, v204
	v_pk_mul_f32 v[204:205], v[32:33], s[8:9] op_sel_hi:[1,0]
	v_exp_f32_e32 v211, v0
	v_min_f32_e32 v0, 0x41e6d4ca, v207
	v_exp_f32_e32 v210, v0
	v_min_f32_e32 v0, 0x41e6d4ca, v204
	v_exp_f32_e32 v207, v0
	v_min_f32_e32 v0, 0x41e6d4ca, v205
	v_exp_f32_e32 v206, v0
	v_pk_add_f32 v[204:205], v[210:211], 1.0 op_sel_hi:[1,0]
	v_lshlrev_b64 v[208:209], 1, v[208:209]
	v_pk_add_f32 v[206:207], v[206:207], 1.0 op_sel_hi:[1,0]
	v_mul_f32_e32 v210, v205, v204
	v_mul_f32_e32 v211, v207, v206
	v_mul_f32_e32 v0, v210, v211
	v_rcp_f32_e32 v203, v0
	v_lshl_add_u64 v[176:177], v[176:177], 0, v[208:209]
	v_mul_f32_e32 v210, v210, v203
	v_pk_mul_f32 v[206:207], v[206:207], v[210:211] op_sel_hi:[1,0]
	v_mul_f32_e32 v0, v211, v203
	v_pk_mul_f32 v[206:207], v[32:33], v[206:207]
	v_pk_mul_f32 v[212:213], v[26:27], s[8:9] op_sel_hi:[1,0]
	v_pk_mul_f32 v[204:205], v[204:205], v[0:1] op_sel_hi:[1,0]
	v_min_f32_e32 v0, 0x41e6d4ca, v212
	v_pk_mul_f32 v[204:205], v[30:31], v[204:205]
	v_pk_mul_f32 v[210:211], v[28:29], s[8:9] op_sel_hi:[1,0]
	v_exp_f32_e32 v217, v0
	v_min_f32_e32 v0, 0x41e6d4ca, v213
	v_exp_f32_e32 v216, v0
	v_min_f32_e32 v0, 0x41e6d4ca, v210
	v_exp_f32_e32 v213, v0
	v_min_f32_e32 v0, 0x41e6d4ca, v211
	v_exp_f32_e32 v212, v0
	v_pk_add_f32 v[210:211], v[216:217], 1.0 op_sel_hi:[1,0]
	v_cvt_pk_bf16_f32 v204, v204, v205
	v_pk_add_f32 v[212:213], v[212:213], 1.0 op_sel_hi:[1,0]
	v_mul_f32_e32 v216, v211, v210
	v_mul_f32_e32 v217, v213, v212
	v_mul_f32_e32 v0, v216, v217
	v_rcp_f32_e32 v203, v0
	v_cvt_pk_bf16_f32 v205, v206, v207
	v_mul_f32_e32 v0, v217, v203
	v_mul_f32_e32 v216, v216, v203
	v_pk_mul_f32 v[210:211], v[210:211], v[0:1] op_sel_hi:[1,0]
	v_pk_mul_f32 v[212:213], v[212:213], v[216:217] op_sel_hi:[1,0]
	v_pk_mul_f32 v[212:213], v[28:29], v[212:213]
	v_pk_mul_f32 v[210:211], v[26:27], v[210:211]
	v_cvt_pk_bf16_f32 v207, v212, v213
	v_cvt_pk_bf16_f32 v206, v210, v211
	v_lshl_add_u64 v[210:211], v[174:175], 0, v[208:209]
	global_store_dwordx4 v[210:211], v[204:207], off
	s_nop 1
	v_pk_mul_f32 v[206:207], v[22:23], s[8:9] op_sel_hi:[1,0]
	v_pk_mul_f32 v[204:205], v[24:25], s[8:9] op_sel_hi:[1,0]
	v_min_f32_e32 v0, 0x41e6d4ca, v206
	v_exp_f32_e32 v211, v0
	v_min_f32_e32 v0, 0x41e6d4ca, v207
	v_exp_f32_e32 v210, v0
	v_min_f32_e32 v0, 0x41e6d4ca, v204
	v_exp_f32_e32 v207, v0
	v_min_f32_e32 v0, 0x41e6d4ca, v205
	v_exp_f32_e32 v206, v0
	v_pk_add_f32 v[204:205], v[210:211], 1.0 op_sel_hi:[1,0]
	v_pk_add_f32 v[206:207], v[206:207], 1.0 op_sel_hi:[1,0]
	v_mul_f32_e32 v210, v205, v204
	v_mul_f32_e32 v211, v207, v206
	v_mul_f32_e32 v0, v210, v211
	v_rcp_f32_e32 v203, v0
	s_nop 0
	v_mul_f32_e32 v210, v210, v203
	v_pk_mul_f32 v[206:207], v[206:207], v[210:211] op_sel_hi:[1,0]
	v_mul_f32_e32 v0, v211, v203
	v_pk_mul_f32 v[206:207], v[24:25], v[206:207]
	v_pk_mul_f32 v[212:213], v[18:19], s[8:9] op_sel_hi:[1,0]
	v_pk_mul_f32 v[204:205], v[204:205], v[0:1] op_sel_hi:[1,0]
	v_min_f32_e32 v0, 0x41e6d4ca, v212
	v_pk_mul_f32 v[204:205], v[22:23], v[204:205]
	v_pk_mul_f32 v[210:211], v[20:21], s[8:9] op_sel_hi:[1,0]
	v_exp_f32_e32 v217, v0
	v_min_f32_e32 v0, 0x41e6d4ca, v213
	v_exp_f32_e32 v216, v0
	v_min_f32_e32 v0, 0x41e6d4ca, v210
	v_exp_f32_e32 v213, v0
	v_min_f32_e32 v0, 0x41e6d4ca, v211
	v_exp_f32_e32 v212, v0
	v_pk_add_f32 v[210:211], v[216:217], 1.0 op_sel_hi:[1,0]
	v_cvt_pk_bf16_f32 v204, v204, v205
	v_pk_add_f32 v[212:213], v[212:213], 1.0 op_sel_hi:[1,0]
	v_mul_f32_e32 v216, v211, v210
	v_mul_f32_e32 v217, v213, v212
	v_mul_f32_e32 v0, v216, v217
	v_rcp_f32_e32 v203, v0
	v_cvt_pk_bf16_f32 v205, v206, v207
	v_mul_f32_e32 v0, v217, v203
	v_mul_f32_e32 v216, v216, v203
	v_pk_mul_f32 v[210:211], v[210:211], v[0:1] op_sel_hi:[1,0]
	v_pk_mul_f32 v[212:213], v[212:213], v[216:217] op_sel_hi:[1,0]
	v_pk_mul_f32 v[212:213], v[20:21], v[212:213]
	v_pk_mul_f32 v[210:211], v[18:19], v[210:211]
	v_cvt_pk_bf16_f32 v207, v212, v213
	v_cvt_pk_bf16_f32 v206, v210, v211
	v_add_u32_e32 v0, 0xb0, v202
	global_store_dwordx4 v[176:177], v[204:207], off
	v_ashrrev_i32_e32 v176, 31, v0
	v_mul_lo_u32 v203, s56, v176
	v_pk_mul_f32 v[206:207], v[14:15], s[8:9] op_sel_hi:[1,0]
	v_mul_lo_u32 v204, s57, v0
	v_mad_u64_u32 v[176:177], s[10:11], s56, v0, 0
	v_min_f32_e32 v0, 0x41e6d4ca, v206
	v_add3_u32 v177, v177, v203, v204
	v_pk_mul_f32 v[204:205], v[16:17], s[8:9] op_sel_hi:[1,0]
	v_exp_f32_e32 v209, v0
	v_min_f32_e32 v0, 0x41e6d4ca, v207
	v_exp_f32_e32 v208, v0
	v_min_f32_e32 v0, 0x41e6d4ca, v204
	v_exp_f32_e32 v207, v0
	v_min_f32_e32 v0, 0x41e6d4ca, v205
	v_exp_f32_e32 v206, v0
	v_pk_add_f32 v[204:205], v[208:209], 1.0 op_sel_hi:[1,0]
	v_pk_add_f32 v[206:207], v[206:207], 1.0 op_sel_hi:[1,0]
	v_mul_f32_e32 v208, v205, v204
	v_mul_f32_e32 v209, v207, v206
	v_mul_f32_e32 v0, v208, v209
	v_rcp_f32_e32 v203, v0
	s_nop 0
	v_mul_f32_e32 v208, v208, v203
	v_pk_mul_f32 v[206:207], v[206:207], v[208:209] op_sel_hi:[1,0]
	v_mul_f32_e32 v0, v209, v203
	v_pk_mul_f32 v[144:145], v[16:17], v[206:207]
	v_pk_mul_f32 v[206:207], v[10:11], s[8:9] op_sel_hi:[1,0]
	v_pk_mul_f32 v[204:205], v[204:205], v[0:1] op_sel_hi:[1,0]
	v_min_f32_e32 v0, 0x41e6d4ca, v206
	v_pk_mul_f32 v[142:143], v[14:15], v[204:205]
	v_pk_mul_f32 v[204:205], v[12:13], s[8:9] op_sel_hi:[1,0]
	v_exp_f32_e32 v209, v0
	v_min_f32_e32 v0, 0x41e6d4ca, v207
	v_exp_f32_e32 v208, v0
	v_min_f32_e32 v0, 0x41e6d4ca, v204
	v_exp_f32_e32 v207, v0
	v_min_f32_e32 v0, 0x41e6d4ca, v205
	v_exp_f32_e32 v206, v0
	v_pk_add_f32 v[204:205], v[208:209], 1.0 op_sel_hi:[1,0]
	v_pk_add_f32 v[206:207], v[206:207], 1.0 op_sel_hi:[1,0]
	v_mul_f32_e32 v208, v205, v204
	s_nop 0
	v_mul_f32_e32 v209, v207, v206
	v_mul_f32_e32 v0, v208, v209
	v_rcp_f32_e32 v203, v0
	s_mov_b64 s[10:11], 0
	v_mul_f32_e32 v0, v209, v203
	v_mul_f32_e32 v208, v208, v203
	v_pk_mul_f32 v[204:205], v[204:205], v[0:1] op_sel_hi:[1,0]
	v_pk_mul_f32 v[206:207], v[206:207], v[208:209] op_sel_hi:[1,0]
	s_nop 0
	v_pk_mul_f32 v[206:207], v[12:13], v[206:207]
	v_pk_mul_f32 v[140:141], v[10:11], v[204:205]
	v_cvt_pk_bf16_f32 v138, v142, v143
	v_cvt_pk_bf16_f32 v139, v144, v145
	v_cvt_pk_bf16_f32 v140, v140, v141
	v_cvt_pk_bf16_f32 v141, v206, v207
	v_lshl_add_u64 v[142:143], v[176:177], 1, v[174:175]
	global_store_dwordx4 v[142:143], v[138:141], off
	s_nop 1
	v_pk_mul_f32 v[140:141], v[6:7], s[8:9] op_sel_hi:[1,0]
	v_pk_mul_f32 v[138:139], v[8:9], s[8:9] op_sel_hi:[1,0]
	v_min_f32_e32 v0, 0x41e6d4ca, v140
	v_exp_f32_e32 v143, v0
	v_min_f32_e32 v0, 0x41e6d4ca, v141
	v_exp_f32_e32 v142, v0
	v_min_f32_e32 v0, 0x41e6d4ca, v138
	v_exp_f32_e32 v141, v0
	v_min_f32_e32 v0, 0x41e6d4ca, v139
	v_exp_f32_e32 v140, v0
	v_pk_add_f32 v[138:139], v[142:143], 1.0 op_sel_hi:[1,0]
	v_pk_add_f32 v[140:141], v[140:141], 1.0 op_sel_hi:[1,0]
	v_mul_f32_e32 v142, v139, v138
	v_mul_f32_e32 v143, v141, v140
	s_nop 0
	v_mul_f32_e32 v0, v142, v143
	v_rcp_f32_e32 v144, v0
	s_nop 0
	v_mul_f32_e32 v0, v143, v144
	v_pk_mul_f32 v[138:139], v[138:139], v[0:1] op_sel_hi:[1,0]
	v_mul_f32_e32 v142, v142, v144
	v_pk_mul_f32 v[134:135], v[6:7], v[138:139]
	v_pk_mul_f32 v[138:139], v[2:3], s[8:9] op_sel_hi:[1,0]
	v_pk_mul_f32 v[140:141], v[140:141], v[142:143] op_sel_hi:[1,0]
	v_min_f32_e32 v0, 0x41e6d4ca, v138
	v_pk_mul_f32 v[140:141], v[8:9], v[140:141]
	v_pk_mul_f32 v[136:137], v[4:5], s[8:9] op_sel_hi:[1,0]
	v_exp_f32_e32 v143, v0
	v_min_f32_e32 v0, 0x41e6d4ca, v139
	v_exp_f32_e32 v142, v0
	v_min_f32_e32 v0, 0x41e6d4ca, v136
	v_exp_f32_e32 v139, v0
	v_min_f32_e32 v0, 0x41e6d4ca, v137
	v_exp_f32_e32 v138, v0
	v_pk_add_f32 v[136:137], v[142:143], 1.0 op_sel_hi:[1,0]
	v_pk_add_f32 v[138:139], v[138:139], 1.0 op_sel_hi:[1,0]
	v_mul_f32_e32 v142, v137, v136
	v_mul_f32_e32 v143, v139, v138
	s_nop 0
	v_mul_f32_e32 v0, v142, v143
	v_rcp_f32_e32 v144, v0
	s_nop 0
	v_mul_f32_e32 v0, v143, v144
	v_mul_f32_e32 v142, v142, v144
	v_pk_mul_f32 v[144:145], v[136:137], v[0:1] op_sel_hi:[1,0]
	v_pk_mul_f32 v[136:137], v[138:139], v[142:143] op_sel_hi:[1,0]
	s_nop 0
	v_pk_mul_f32 v[136:137], v[4:5], v[136:137]
	v_pk_mul_f32 v[132:133], v[2:3], v[144:145]
	v_cvt_pk_bf16_f32 v130, v134, v135
	v_cvt_pk_bf16_f32 v131, v140, v141
	v_cvt_pk_bf16_f32 v132, v132, v133
